# GEMM K-loops: per-workgroup rotation of the K-step order (steps 1..31 start at an offset derived from the row-tile group) so lock-stepped workgroups with 4 KB row pitch hit different L2 channels; accu
# speedup vs baseline: 1.0395x; 1.0156x over previous
.LBB0_261:
	s_ashr_i32 s79, s78, 31
	s_lshl_b64 s[2:3], s[78:79], 12
	s_lshl_b32 s78, s14, 8
	s_mov_b64 s[82:83], -1
	s_and_b64 vcc, exec, s[80:81]
	s_cbranch_vccz .LBB0_287
	v_mov_b32_e32 v10, v156
	s_add_u32 s14, s4, s2
	s_addc_u32 s15, s5, s3
	v_ashrrev_i32_e32 v0, 3, v10
	s_add_i32 s80, s78, 0x400
	v_xor_b32_e32 v6, v0, v10
	v_ashrrev_i32_e32 v1, 31, v0
	s_ashr_i32 s81, s80, 31
	v_lshlrev_b64 v[2:3], 12, v[0:1]
	v_lshlrev_b32_e32 v1, 4, v6
	s_lshl_b64 s[80:81], s[80:81], 12
	v_and_b32_e32 v144, 0x70, v1
	v_lshlrev_b32_e32 v1, 4, v10
	s_add_u32 s82, s70, s80
	v_add_u32_e32 v139, 0, v1
	s_addc_u32 s83, s71, s81
	v_lshl_add_u64 v[4:5], s[14:15], 0, v[2:3]
	v_add_u32_e32 v140, s86, v1
	v_readfirstlane_b32 s14, v139
	v_lshl_add_u64 v[4:5], v[4:5], 0, v[144:145]
	v_lshl_add_u64 v[6:7], s[82:83], 0, v[2:3]
	s_mov_b32 m0, s14
	v_readfirstlane_b32 s14, v140
	v_add_u32_e32 v1, 0x2000, v139
	v_lshl_add_u64 v[6:7], v[6:7], 0, v[144:145]
	s_barrier
	global_load_lds_dwordx4 v[4:5], off
	s_mov_b32 m0, s14
	v_readfirstlane_b32 s14, v1
	v_add_u32_e32 v1, 0x2000, v140
	global_load_lds_dwordx4 v[6:7], off
	v_lshl_add_u64 v[8:9], v[4:5], 0, s[50:51]
	s_mov_b32 m0, s14
	v_readfirstlane_b32 s14, v1
	v_add_u32_e32 v1, 0x4000, v139
	global_load_lds_dwordx4 v[8:9], off
	v_lshl_add_u64 v[8:9], v[6:7], 0, s[50:51]
	s_mov_b32 m0, s14
	v_readfirstlane_b32 s14, v1
	v_add_u32_e32 v1, 0x4000, v140
	global_load_lds_dwordx4 v[8:9], off
	v_lshl_add_u64 v[8:9], v[4:5], 0, s[54:55]
	s_mov_b32 m0, s14
	v_readfirstlane_b32 s14, v1
	v_add_u32_e32 v1, 0x6000, v139
	global_load_lds_dwordx4 v[8:9], off
	v_lshl_add_u64 v[8:9], v[6:7], 0, s[54:55]
	s_mov_b32 m0, s14
	v_readfirstlane_b32 s14, v1
	v_add_u32_e32 v1, 0x6000, v140
	global_load_lds_dwordx4 v[8:9], off
	v_lshl_add_u64 v[4:5], v[4:5], 0, s[56:57]
	s_mov_b32 m0, s14
	v_readfirstlane_b32 s14, v1
	global_load_lds_dwordx4 v[4:5], off
	v_lshl_add_u64 v[4:5], v[6:7], 0, s[56:57]
	s_mov_b32 m0, s14
	v_ashrrev_i32_e32 v1, 1, v10
	global_load_lds_dwordx4 v[4:5], off
	v_and_b32_e32 v133, 15, v10
	v_and_b32_e32 v135, 0xffffffc0, v1
	v_bfe_u32 v132, v10, 6, 1
	v_lshrrev_b32_e32 v11, 4, v10
	v_or_b32_e32 v1, v135, v133
	v_and_b32_e32 v6, 7, v10
	v_bfe_u32 v134, v10, 4, 2
	v_lshlrev_b32_e32 v4, 13, v132
	v_lshlrev_b32_e32 v5, 7, v133
	v_lshl_add_u32 v137, v1, 7, 0
	v_bitop3_b32 v1, v11, v6, 3 bitop3:0x6c
	v_bitop3_b32 v0, v0, 7, v10 bitop3:0x48
	v_add3_u32 v136, s86, v4, v5
	v_lshlrev_b32_e32 v141, 4, v1
	v_bitop3_b32 v1, v134, v6, 4 bitop3:0x36
	v_lshl_add_u64 v[4:5], v[2:3], 0, s[2:3]
	v_lshlrev_b32_e32 v144, 4, v0
	v_lshlrev_b32_e32 v138, 4, v1
	v_lshl_add_u64 v[0:1], v[4:5], 0, v[144:145]
	v_lshl_add_u64 v[128:129], s[72:73], 0, v[0:1]
	v_lshl_add_u64 v[0:1], v[2:3], 0, s[80:81]
	s_waitcnt vmcnt(0)
	v_or_b32_e32 v0, v0, v144
	v_lshl_add_u64 v[130:131], s[72:73], 0, v[0:1]
	v_mov_b32_e32 v0, 0
	s_mov_b32 s14, 0
	s_mov_b64 s[80:81], 0
	v_mov_b32_e32 v1, v0
	v_mov_b32_e32 v2, v0
	v_mov_b32_e32 v3, v0
	v_mov_b32_e32 v4, v0
	v_mov_b32_e32 v5, v0
	v_mov_b32_e32 v6, v0
	v_mov_b32_e32 v7, v0
	v_mov_b32_e32 v8, v0
	v_mov_b32_e32 v9, v0
	v_mov_b32_e32 v10, v0
	v_mov_b32_e32 v11, v0
	v_mov_b32_e32 v12, v0
	v_mov_b32_e32 v13, v0
	v_mov_b32_e32 v14, v0
	v_mov_b32_e32 v15, v0
	v_mov_b32_e32 v16, v0
	v_mov_b32_e32 v17, v0
	v_mov_b32_e32 v18, v0
	v_mov_b32_e32 v19, v0
	v_mov_b32_e32 v20, v0
	v_mov_b32_e32 v21, v0
	v_mov_b32_e32 v22, v0
	v_mov_b32_e32 v23, v0
	v_mov_b32_e32 v24, v0
	v_mov_b32_e32 v25, v0
	v_mov_b32_e32 v26, v0
	v_mov_b32_e32 v27, v0
	v_mov_b32_e32 v28, v0
	v_mov_b32_e32 v29, v0
	v_mov_b32_e32 v30, v0
	v_mov_b32_e32 v31, v0
	v_mov_b32_e32 v32, v0
	v_mov_b32_e32 v33, v0
	v_mov_b32_e32 v34, v0
	v_mov_b32_e32 v35, v0
	v_mov_b32_e32 v36, v0
	v_mov_b32_e32 v37, v0
	v_mov_b32_e32 v38, v0
	v_mov_b32_e32 v39, v0
	v_mov_b32_e32 v40, v0
	v_mov_b32_e32 v41, v0
	v_mov_b32_e32 v42, v0
	v_mov_b32_e32 v43, v0
	v_mov_b32_e32 v44, v0
	v_mov_b32_e32 v45, v0
	v_mov_b32_e32 v46, v0
	v_mov_b32_e32 v47, v0
	v_mov_b32_e32 v48, v0
	v_mov_b32_e32 v49, v0
	v_mov_b32_e32 v50, v0
	v_mov_b32_e32 v51, v0
	v_mov_b32_e32 v52, v0
	v_mov_b32_e32 v53, v0
	v_mov_b32_e32 v54, v0
	v_mov_b32_e32 v55, v0
	v_mov_b32_e32 v56, v0
	v_mov_b32_e32 v57, v0
	v_mov_b32_e32 v58, v0
	v_mov_b32_e32 v59, v0
	v_mov_b32_e32 v60, v0
	v_mov_b32_e32 v61, v0
	v_mov_b32_e32 v62, v0
	v_mov_b32_e32 v63, v0
	v_mov_b32_e32 v64, v0
	v_mov_b32_e32 v65, v0
	v_mov_b32_e32 v66, v0
	v_mov_b32_e32 v67, v0
	v_mov_b32_e32 v68, v0
	v_mov_b32_e32 v69, v0
	v_mov_b32_e32 v70, v0
	v_mov_b32_e32 v71, v0
	v_mov_b32_e32 v72, v0
	v_mov_b32_e32 v73, v0
	v_mov_b32_e32 v74, v0
	v_mov_b32_e32 v75, v0
	v_mov_b32_e32 v76, v0
	v_mov_b32_e32 v77, v0
	v_mov_b32_e32 v78, v0
	v_mov_b32_e32 v79, v0
	v_mov_b32_e32 v80, v0
	v_mov_b32_e32 v81, v0
	v_mov_b32_e32 v82, v0
	v_mov_b32_e32 v83, v0
	v_mov_b32_e32 v84, v0
	v_mov_b32_e32 v85, v0
	v_mov_b32_e32 v86, v0
	v_mov_b32_e32 v87, v0
	v_mov_b32_e32 v88, v0
	v_mov_b32_e32 v89, v0
	v_mov_b32_e32 v90, v0
	v_mov_b32_e32 v91, v0
	v_mov_b32_e32 v92, v0
	v_mov_b32_e32 v93, v0
	v_mov_b32_e32 v94, v0
	v_mov_b32_e32 v95, v0
	v_mov_b32_e32 v96, v0
	v_mov_b32_e32 v97, v0
	v_mov_b32_e32 v98, v0
	v_mov_b32_e32 v99, v0
	v_mov_b32_e32 v100, v0
	v_mov_b32_e32 v101, v0
	v_mov_b32_e32 v102, v0
	v_mov_b32_e32 v103, v0
	v_mov_b32_e32 v104, v0
	v_mov_b32_e32 v105, v0
	v_mov_b32_e32 v106, v0
	v_mov_b32_e32 v107, v0
	v_mov_b32_e32 v108, v0
	v_mov_b32_e32 v109, v0
	v_mov_b32_e32 v110, v0
	v_mov_b32_e32 v111, v0
	v_mov_b32_e32 v112, v0
	v_mov_b32_e32 v113, v0
	v_mov_b32_e32 v114, v0
	v_mov_b32_e32 v115, v0
	v_mov_b32_e32 v116, v0
	v_mov_b32_e32 v117, v0
	v_mov_b32_e32 v118, v0
	v_mov_b32_e32 v119, v0
	v_mov_b32_e32 v120, v0
	v_mov_b32_e32 v121, v0
	v_mov_b32_e32 v122, v0
	v_mov_b32_e32 v123, v0
	v_mov_b32_e32 v124, v0
	v_mov_b32_e32 v125, v0
	v_mov_b32_e32 v126, v0
	v_mov_b32_e32 v127, v0
	s_waitcnt vmcnt(0) lgkmcnt(0)
	s_barrier
	v_readfirstlane_b32 s98, v139
	v_readfirstlane_b32 s99, v140
	s_and_b32 s15, s14, 0x8000
	s_xor_b32 s22, s15, 0x8000
	v_add3_u32 v142, v137, v141, s15
	v_add3_u32 v143, v136, v141, s15
	ds_read_b128 v[174:177], v142
	ds_read_b128 v[178:181], v142 offset:2048
	ds_read_b128 v[182:185], v142 offset:4096
	ds_read_b128 v[186:189], v142 offset:6144
	ds_read_b128 v[158:161], v143
	ds_read_b128 v[162:165], v143 offset:2048
	ds_read_b128 v[166:169], v143 offset:4096
	ds_read_b128 v[170:173], v143 offset:6144
	s_add_i32 s100, s98, s22
	s_add_i32 s101, s99, s22
	s_lshr_b32 s22, s23, 3
	s_and_b32 s22, s22, 7
	s_lshl_b32 s22, s22, 9
	s_add_i32 vcc_lo, s80, s22
	s_cmp_ge_u32 vcc_lo, 0xf80
	s_cselect_b32 vcc_hi, 0xf80, 0
	s_sub_i32 vcc_lo, vcc_lo, vcc_hi
	s_add_u32 s82, vcc_lo, 0x7870080
	s_addc_u32 s83, 0, 0
	s_add_i32 m0, s100, 0x0
	v_lshl_add_u64 v[146:147], v[128:129], 0, s[82:83]
	global_load_lds_dwordx4 v[146:147], off
	s_add_u32 s82, vcc_lo, s58
	s_addc_u32 s83, 0, s59
	s_add_i32 m0, s101, 0x0
	v_lshl_add_u64 v[146:147], v[130:131], 0, s[82:83]
	global_load_lds_dwordx4 v[146:147], off
	s_add_u32 s82, vcc_lo, 0x78b0080
	s_addc_u32 s83, 0, 0
	s_add_i32 m0, s100, 0x2000
	v_lshl_add_u64 v[146:147], v[128:129], 0, s[82:83]
	global_load_lds_dwordx4 v[146:147], off
	s_add_u32 s82, vcc_lo, s60
	s_addc_u32 s83, 0, s61
	s_add_i32 m0, s101, 0x2000
	v_lshl_add_u64 v[146:147], v[130:131], 0, s[82:83]
	global_load_lds_dwordx4 v[146:147], off
	s_add_u32 s82, vcc_lo, 0x78f0080
	s_addc_u32 s83, 0, 0
	s_add_i32 m0, s100, 0x4000
	v_lshl_add_u64 v[146:147], v[128:129], 0, s[82:83]
	global_load_lds_dwordx4 v[146:147], off
	s_add_u32 s82, vcc_lo, s62
	s_addc_u32 s83, 0, s63
	s_add_i32 m0, s101, 0x4000
	v_lshl_add_u64 v[146:147], v[130:131], 0, s[82:83]
	global_load_lds_dwordx4 v[146:147], off
	s_add_u32 s82, vcc_lo, 0x7930080
	s_addc_u32 s83, 0, 0
	s_add_i32 m0, s100, 0x6000
	v_lshl_add_u64 v[146:147], v[128:129], 0, s[82:83]
	global_load_lds_dwordx4 v[146:147], off
	s_add_u32 s82, vcc_lo, s64
	s_addc_u32 s83, 0, s65
	s_add_i32 m0, s101, 0x6000
	v_lshl_add_u64 v[146:147], v[130:131], 0, s[82:83]
	global_load_lds_dwordx4 v[146:147], off
.LBB0_263:
	s_and_b32 s15, s14, 0x8000
	s_add_i32 s14, s14, 0x8000
	v_add3_u32 v142, v137, v138, s15
	v_add3_u32 v143, v136, v141, s15
	v_add3_u32 v144, v136, v138, s15
	s_waitcnt lgkmcnt(3)
	v_mfma_f32_16x16x32_bf16 v[124:127], v[174:177], v[158:161], v[124:127]
	v_mfma_f32_16x16x32_bf16 v[92:95], v[178:181], v[158:161], v[92:95]
	v_mfma_f32_16x16x32_bf16 v[60:63], v[182:185], v[158:161], v[60:63]
	v_mfma_f32_16x16x32_bf16 v[28:31], v[186:189], v[158:161], v[28:31]
	ds_read_b128 v[158:161], v143 offset:16384
	ds_read_b128 v[190:193], v142
	s_waitcnt lgkmcnt(4)
	v_mfma_f32_16x16x32_bf16 v[120:123], v[174:177], v[162:165], v[120:123]
	v_mfma_f32_16x16x32_bf16 v[88:91], v[178:181], v[162:165], v[88:91]
	v_mfma_f32_16x16x32_bf16 v[56:59], v[182:185], v[162:165], v[56:59]
	v_mfma_f32_16x16x32_bf16 v[24:27], v[186:189], v[162:165], v[24:27]
	ds_read_b128 v[162:165], v143 offset:18432
	ds_read_b128 v[194:197], v142 offset:2048
	s_waitcnt lgkmcnt(5)
	v_mfma_f32_16x16x32_bf16 v[116:119], v[174:177], v[166:169], v[116:119]
	v_mfma_f32_16x16x32_bf16 v[84:87], v[178:181], v[166:169], v[84:87]
	v_mfma_f32_16x16x32_bf16 v[52:55], v[182:185], v[166:169], v[52:55]
	v_mfma_f32_16x16x32_bf16 v[20:23], v[186:189], v[166:169], v[20:23]
	ds_read_b128 v[166:169], v143 offset:20480
	ds_read_b128 v[198:201], v142 offset:4096
	s_waitcnt lgkmcnt(6)
	v_mfma_f32_16x16x32_bf16 v[112:115], v[174:177], v[170:173], v[112:115]
	v_mfma_f32_16x16x32_bf16 v[80:83], v[178:181], v[170:173], v[80:83]
	v_mfma_f32_16x16x32_bf16 v[48:51], v[182:185], v[170:173], v[48:51]
	v_mfma_f32_16x16x32_bf16 v[16:19], v[186:189], v[170:173], v[16:19]
	ds_read_b128 v[170:173], v143 offset:22528
	ds_read_b128 v[150:153], v142 offset:6144
	s_waitcnt lgkmcnt(7)
	v_mfma_f32_16x16x32_bf16 v[108:111], v[174:177], v[158:161], v[108:111]
	v_mfma_f32_16x16x32_bf16 v[76:79], v[178:181], v[158:161], v[76:79]
	v_mfma_f32_16x16x32_bf16 v[44:47], v[182:185], v[158:161], v[44:47]
	v_mfma_f32_16x16x32_bf16 v[12:15], v[186:189], v[158:161], v[12:15]
	ds_read_b128 v[158:161], v144
	s_waitcnt lgkmcnt(6)
	v_mfma_f32_16x16x32_bf16 v[104:107], v[174:177], v[162:165], v[104:107]
	v_mfma_f32_16x16x32_bf16 v[72:75], v[178:181], v[162:165], v[72:75]
	v_mfma_f32_16x16x32_bf16 v[40:43], v[182:185], v[162:165], v[40:43]
	v_mfma_f32_16x16x32_bf16 v[8:11], v[186:189], v[162:165], v[8:11]
	ds_read_b128 v[162:165], v144 offset:2048
	s_waitcnt lgkmcnt(5)
	v_mfma_f32_16x16x32_bf16 v[100:103], v[174:177], v[166:169], v[100:103]
	v_mfma_f32_16x16x32_bf16 v[68:71], v[178:181], v[166:169], v[68:71]
	v_mfma_f32_16x16x32_bf16 v[36:39], v[182:185], v[166:169], v[36:39]
	v_mfma_f32_16x16x32_bf16 v[4:7], v[186:189], v[166:169], v[4:7]
	ds_read_b128 v[166:169], v144 offset:4096
	s_waitcnt lgkmcnt(4)
	v_mfma_f32_16x16x32_bf16 v[96:99], v[174:177], v[170:173], v[96:99]
	v_mfma_f32_16x16x32_bf16 v[64:67], v[178:181], v[170:173], v[64:67]
	v_mfma_f32_16x16x32_bf16 v[32:35], v[182:185], v[170:173], v[32:35]
	v_mfma_f32_16x16x32_bf16 v[0:3], v[186:189], v[170:173], v[0:3]
	ds_read_b128 v[170:173], v144 offset:6144
	s_waitcnt lgkmcnt(3)
	v_mfma_f32_16x16x32_bf16 v[124:127], v[190:193], v[158:161], v[124:127]
	v_mfma_f32_16x16x32_bf16 v[92:95], v[194:197], v[158:161], v[92:95]
	v_mfma_f32_16x16x32_bf16 v[60:63], v[198:201], v[158:161], v[60:63]
	v_mfma_f32_16x16x32_bf16 v[28:31], v[150:153], v[158:161], v[28:31]
	ds_read_b128 v[158:161], v144 offset:16384
	s_waitcnt lgkmcnt(3)
	v_mfma_f32_16x16x32_bf16 v[120:123], v[190:193], v[162:165], v[120:123]
	v_mfma_f32_16x16x32_bf16 v[88:91], v[194:197], v[162:165], v[88:91]
	v_mfma_f32_16x16x32_bf16 v[56:59], v[198:201], v[162:165], v[56:59]
	v_mfma_f32_16x16x32_bf16 v[24:27], v[150:153], v[162:165], v[24:27]
	ds_read_b128 v[162:165], v144 offset:18432
	s_waitcnt lgkmcnt(3)
	v_mfma_f32_16x16x32_bf16 v[116:119], v[190:193], v[166:169], v[116:119]
	v_mfma_f32_16x16x32_bf16 v[84:87], v[194:197], v[166:169], v[84:87]
	v_mfma_f32_16x16x32_bf16 v[52:55], v[198:201], v[166:169], v[52:55]
	v_mfma_f32_16x16x32_bf16 v[20:23], v[150:153], v[166:169], v[20:23]
	ds_read_b128 v[166:169], v144 offset:20480
	s_waitcnt lgkmcnt(3)
	v_mfma_f32_16x16x32_bf16 v[112:115], v[190:193], v[170:173], v[112:115]
	v_mfma_f32_16x16x32_bf16 v[80:83], v[194:197], v[170:173], v[80:83]
	v_mfma_f32_16x16x32_bf16 v[48:51], v[198:201], v[170:173], v[48:51]
	v_mfma_f32_16x16x32_bf16 v[16:19], v[150:153], v[170:173], v[16:19]
	ds_read_b128 v[170:173], v144 offset:22528
	s_waitcnt lgkmcnt(3)
	v_mfma_f32_16x16x32_bf16 v[108:111], v[190:193], v[158:161], v[108:111]
	v_mfma_f32_16x16x32_bf16 v[76:79], v[194:197], v[158:161], v[76:79]
	v_mfma_f32_16x16x32_bf16 v[44:47], v[198:201], v[158:161], v[44:47]
	v_mfma_f32_16x16x32_bf16 v[12:15], v[150:153], v[158:161], v[12:15]
	s_add_u32 s80, s80, 0x80
	s_addc_u32 s81, s81, 0
	s_cmpk_eq_i32 s80, 0xf80
	s_waitcnt vmcnt(0) lgkmcnt(0)
	s_barrier
	s_cbranch_scc1 .Lgemm_263_exit
	s_xor_b32 s22, s15, 0x8000
	v_add3_u32 v142, v137, v141, s22
	v_add3_u32 v143, v136, v141, s22
	ds_read_b128 v[174:177], v142
	ds_read_b128 v[178:181], v142 offset:2048
	ds_read_b128 v[182:185], v142 offset:4096
	ds_read_b128 v[186:189], v142 offset:6144
	ds_read_b128 v[158:161], v143
	s_add_i32 s100, s98, s15
	s_add_i32 s101, s99, s15
	s_lshr_b32 s22, s23, 3
	s_and_b32 s22, s22, 7
	s_lshl_b32 s22, s22, 9
	s_add_i32 vcc_lo, s80, s22
	s_cmp_ge_u32 vcc_lo, 0xf80
	s_cselect_b32 vcc_hi, 0xf80, 0
	s_sub_i32 vcc_lo, vcc_lo, vcc_hi
	s_add_u32 s82, vcc_lo, 0x7870080
	s_addc_u32 s83, 0, 0
	s_add_i32 m0, s100, 0x0
	v_lshl_add_u64 v[146:147], v[128:129], 0, s[82:83]
	global_load_lds_dwordx4 v[146:147], off
	s_add_u32 s82, vcc_lo, s58
	s_addc_u32 s83, 0, s59
	s_add_i32 m0, s101, 0x0
	v_lshl_add_u64 v[146:147], v[130:131], 0, s[82:83]
	global_load_lds_dwordx4 v[146:147], off
	v_mfma_f32_16x16x32_bf16 v[104:107], v[190:193], v[162:165], v[104:107]
	v_mfma_f32_16x16x32_bf16 v[72:75], v[194:197], v[162:165], v[72:75]
	v_mfma_f32_16x16x32_bf16 v[40:43], v[198:201], v[162:165], v[40:43]
	v_mfma_f32_16x16x32_bf16 v[8:11], v[150:153], v[162:165], v[8:11]
	ds_read_b128 v[162:165], v143 offset:2048
	s_add_u32 s82, vcc_lo, 0x78b0080
	s_addc_u32 s83, 0, 0
	s_add_i32 m0, s100, 0x2000
	v_lshl_add_u64 v[146:147], v[128:129], 0, s[82:83]
	global_load_lds_dwordx4 v[146:147], off
	s_add_u32 s82, vcc_lo, s60
	s_addc_u32 s83, 0, s61
	s_add_i32 m0, s101, 0x2000
	v_lshl_add_u64 v[146:147], v[130:131], 0, s[82:83]
	global_load_lds_dwordx4 v[146:147], off
	v_mfma_f32_16x16x32_bf16 v[100:103], v[190:193], v[166:169], v[100:103]
	v_mfma_f32_16x16x32_bf16 v[68:71], v[194:197], v[166:169], v[68:71]
	v_mfma_f32_16x16x32_bf16 v[36:39], v[198:201], v[166:169], v[36:39]
	v_mfma_f32_16x16x32_bf16 v[4:7], v[150:153], v[166:169], v[4:7]
	ds_read_b128 v[166:169], v143 offset:4096
	s_add_u32 s82, vcc_lo, 0x78f0080
	s_addc_u32 s83, 0, 0
	s_add_i32 m0, s100, 0x4000
	v_lshl_add_u64 v[146:147], v[128:129], 0, s[82:83]
	global_load_lds_dwordx4 v[146:147], off
	s_add_u32 s82, vcc_lo, s62
	s_addc_u32 s83, 0, s63
	s_add_i32 m0, s101, 0x4000
	v_lshl_add_u64 v[146:147], v[130:131], 0, s[82:83]
	global_load_lds_dwordx4 v[146:147], off
	v_mfma_f32_16x16x32_bf16 v[96:99], v[190:193], v[170:173], v[96:99]
	v_mfma_f32_16x16x32_bf16 v[64:67], v[194:197], v[170:173], v[64:67]
	v_mfma_f32_16x16x32_bf16 v[32:35], v[198:201], v[170:173], v[32:35]
	v_mfma_f32_16x16x32_bf16 v[0:3], v[150:153], v[170:173], v[0:3]
	ds_read_b128 v[170:173], v143 offset:6144
	s_add_u32 s82, vcc_lo, 0x7930080
	s_addc_u32 s83, 0, 0
	s_add_i32 m0, s100, 0x6000
	v_lshl_add_u64 v[146:147], v[128:129], 0, s[82:83]
	global_load_lds_dwordx4 v[146:147], off
	s_add_u32 s82, vcc_lo, s64
	s_addc_u32 s83, 0, s65
	s_add_i32 m0, s101, 0x6000
	v_lshl_add_u64 v[146:147], v[130:131], 0, s[82:83]
	global_load_lds_dwordx4 v[146:147], off
	s_branch .LBB0_263

.LBB0_495:
	s_bitcmp1_b32 s33, 2
	s_cselect_b64 s[60:61], -1, 0
	s_lshl_b32 s62, s33, 10
	s_lshl_b32 s4, s8, 13
	s_and_b32 s70, s62, 0x1000
	s_lshl_b32 s62, s33, 21
	s_bfe_u32 s65, s8, 0x20008
	s_and_b32 s4, s4, 0x600000
	s_ashr_i32 s64, s33, 3
	s_and_b32 s62, s62, 0x600000
	s_add_u32 s62, s18, s62
	s_addc_u32 s63, s19, 0
	s_add_u32 s62, s62, s70
	s_addc_u32 s63, s63, 0
	s_lshl_b32 s66, s64, 8
	v_mov_b32_e32 v10, v156
	s_ashr_i32 s67, s66, 31
	s_lshl_b64 s[66:67], s[66:67], 13
	v_ashrrev_i32_e32 v0, 3, v10
	v_xor_b32_e32 v6, v0, v10
	v_ashrrev_i32_e32 v1, 31, v0
	s_add_u32 s68, s0, s66
	v_lshlrev_b64 v[2:3], 13, v[0:1]
	v_lshlrev_b32_e32 v1, 4, v6
	s_addc_u32 s69, s1, s67
	v_and_b32_e32 v132, 0x70, v1
	v_lshlrev_b32_e32 v1, 4, v10
	s_add_u32 s68, s68, s70
	v_add_u32_e32 v140, 0, v1
	s_addc_u32 s69, s69, 0
	v_lshl_add_u64 v[4:5], s[62:63], 0, v[2:3]
	v_add_u32_e32 v141, s14, v1
	v_readfirstlane_b32 s62, v140
	v_lshl_add_u64 v[4:5], v[4:5], 0, v[132:133]
	v_lshl_add_u64 v[6:7], s[68:69], 0, v[2:3]
	s_mov_b32 m0, s62
	v_readfirstlane_b32 s62, v141
	v_add_u32_e32 v1, 0x2000, v140
	v_lshl_add_u64 v[6:7], v[6:7], 0, v[132:133]
	s_barrier
	global_load_lds_dwordx4 v[4:5], off
	s_mov_b32 m0, s62
	v_readfirstlane_b32 s62, v1
	v_add_u32_e32 v1, 0x2000, v141
	global_load_lds_dwordx4 v[6:7], off
	v_lshl_add_u64 v[8:9], v[4:5], 0, s[6:7]
	s_mov_b32 m0, s62
	v_readfirstlane_b32 s62, v1
	v_add_u32_e32 v1, 0x4000, v140
	global_load_lds_dwordx4 v[8:9], off
	v_lshl_add_u64 v[8:9], v[6:7], 0, s[6:7]
	s_mov_b32 m0, s62
	v_readfirstlane_b32 s62, v1
	v_add_u32_e32 v1, 0x4000, v141
	global_load_lds_dwordx4 v[8:9], off
	v_lshl_add_u64 v[8:9], v[4:5], 0, s[26:27]
	s_mov_b32 m0, s62
	v_readfirstlane_b32 s62, v1
	v_add_u32_e32 v1, 0x6000, v140
	global_load_lds_dwordx4 v[8:9], off
	v_lshl_add_u64 v[8:9], v[6:7], 0, s[26:27]
	s_mov_b32 m0, s62
	v_readfirstlane_b32 s62, v1
	v_add_u32_e32 v1, 0x6000, v141
	global_load_lds_dwordx4 v[8:9], off
	v_lshl_add_u64 v[4:5], v[4:5], 0, s[36:37]
	s_mov_b32 m0, s62
	v_readfirstlane_b32 s62, v1
	global_load_lds_dwordx4 v[4:5], off
	v_lshl_add_u64 v[4:5], v[6:7], 0, s[36:37]
	s_mov_b32 m0, s62
	v_ashrrev_i32_e32 v1, 1, v10
	global_load_lds_dwordx4 v[4:5], off
	v_and_b32_e32 v135, 15, v10
	v_and_b32_e32 v136, 0xffffffc0, v1
	v_lshrrev_b32_e32 v11, 4, v10
	v_or_b32_e32 v1, v136, v135
	v_and_b32_e32 v6, 7, v10
	v_bfe_u32 v134, v10, 6, 1
	v_bfe_u32 v132, v10, 4, 2
	v_lshl_add_u32 v137, v1, 7, 0
	v_bitop3_b32 v1, v11, v6, 3 bitop3:0x6c
	v_lshlrev_b32_e32 v4, 13, v134
	v_lshlrev_b32_e32 v5, 7, v135
	v_lshlrev_b32_e32 v142, 4, v1
	v_bitop3_b32 v1, v132, v6, 4 bitop3:0x36
	v_bitop3_b32 v0, v0, 7, v10 bitop3:0x48
	s_waitcnt vmcnt(0)
	v_add3_u32 v139, s14, v4, v5
	v_lshlrev_b32_e32 v138, 4, v1
	v_lshl_add_u64 v[4:5], s[4:5], 0, v[2:3]
	v_lshlrev_b32_e32 v6, 4, v0
	v_lshl_add_u64 v[0:1], v[2:3], 0, s[66:67]
	v_or3_b32 v4, v4, s70, v6
	v_or3_b32 v0, v0, s70, v6
	v_lshl_add_u64 v[128:129], s[72:73], 0, v[4:5]
	v_lshl_add_u64 v[130:131], s[72:73], 0, v[0:1]
	s_mov_b64 s[62:63], 0
	s_mov_b32 s4, 0
	v_mov_b32_e32 v20, 0
	v_mov_b32_e32 v21, v133
	v_mov_b32_e32 v22, v133
	v_mov_b32_e32 v23, v133
	v_mov_b32_e32 v100, 0
	v_mov_b32_e32 v101, v133
	v_mov_b32_e32 v102, v133
	v_mov_b32_e32 v103, v133
	v_mov_b32_e32 v0, 0
	v_mov_b32_e32 v1, v133
	v_mov_b32_e32 v2, v133
	v_mov_b32_e32 v3, v133
	v_mov_b32_e32 v32, 0
	v_mov_b32_e32 v33, v133
	v_mov_b32_e32 v34, v133
	v_mov_b32_e32 v35, v133
	v_mov_b32_e32 v36, 0
	v_mov_b32_e32 v37, v133
	v_mov_b32_e32 v38, v133
	v_mov_b32_e32 v39, v133
	v_mov_b32_e32 v40, 0
	v_mov_b32_e32 v41, v133
	v_mov_b32_e32 v42, v133
	v_mov_b32_e32 v43, v133
	v_mov_b32_e32 v44, 0
	v_mov_b32_e32 v45, v133
	v_mov_b32_e32 v46, v133
	v_mov_b32_e32 v47, v133
	v_mov_b32_e32 v48, 0
	v_mov_b32_e32 v49, v133
	v_mov_b32_e32 v50, v133
	v_mov_b32_e32 v51, v133
	v_mov_b32_e32 v4, 0
	v_mov_b32_e32 v5, v133
	v_mov_b32_e32 v6, v133
	v_mov_b32_e32 v7, v133
	v_mov_b32_e32 v52, 0
	v_mov_b32_e32 v53, v133
	v_mov_b32_e32 v54, v133
	v_mov_b32_e32 v55, v133
	v_mov_b32_e32 v8, 0
	v_mov_b32_e32 v9, v133
	v_mov_b32_e32 v10, v133
	v_mov_b32_e32 v11, v133
	v_mov_b32_e32 v56, 0
	v_mov_b32_e32 v57, v133
	v_mov_b32_e32 v58, v133
	v_mov_b32_e32 v59, v133
	v_mov_b32_e32 v60, 0
	v_mov_b32_e32 v61, v133
	v_mov_b32_e32 v62, v133
	v_mov_b32_e32 v63, v133
	v_mov_b32_e32 v64, 0
	v_mov_b32_e32 v65, v133
	v_mov_b32_e32 v66, v133
	v_mov_b32_e32 v67, v133
	v_mov_b32_e32 v68, 0
	v_mov_b32_e32 v69, v133
	v_mov_b32_e32 v70, v133
	v_mov_b32_e32 v71, v133
	v_mov_b32_e32 v72, 0
	v_mov_b32_e32 v73, v133
	v_mov_b32_e32 v74, v133
	v_mov_b32_e32 v75, v133
	v_mov_b32_e32 v12, 0
	v_mov_b32_e32 v13, v133
	v_mov_b32_e32 v14, v133
	v_mov_b32_e32 v15, v133
	v_mov_b32_e32 v76, 0
	v_mov_b32_e32 v77, v133
	v_mov_b32_e32 v78, v133
	v_mov_b32_e32 v79, v133
	v_mov_b32_e32 v16, 0
	v_mov_b32_e32 v17, v133
	v_mov_b32_e32 v18, v133
	v_mov_b32_e32 v19, v133
	v_mov_b32_e32 v80, 0
	v_mov_b32_e32 v81, v133
	v_mov_b32_e32 v82, v133
	v_mov_b32_e32 v83, v133
	v_mov_b32_e32 v84, 0
	v_mov_b32_e32 v85, v133
	v_mov_b32_e32 v86, v133
	v_mov_b32_e32 v87, v133
	v_mov_b32_e32 v88, 0
	v_mov_b32_e32 v89, v133
	v_mov_b32_e32 v90, v133
	v_mov_b32_e32 v91, v133
	v_mov_b32_e32 v92, 0
	v_mov_b32_e32 v93, v133
	v_mov_b32_e32 v94, v133
	v_mov_b32_e32 v95, v133
	v_mov_b32_e32 v96, 0
	v_mov_b32_e32 v97, v133
	v_mov_b32_e32 v98, v133
	v_mov_b32_e32 v99, v133
	v_mov_b32_e32 v24, 0
	v_mov_b32_e32 v25, v133
	v_mov_b32_e32 v26, v133
	v_mov_b32_e32 v27, v133
	v_mov_b32_e32 v104, 0
	v_mov_b32_e32 v105, v133
	v_mov_b32_e32 v106, v133
	v_mov_b32_e32 v107, v133
	v_mov_b32_e32 v28, 0
	v_mov_b32_e32 v29, v133
	v_mov_b32_e32 v30, v133
	v_mov_b32_e32 v31, v133
	v_mov_b32_e32 v108, 0
	v_mov_b32_e32 v109, v133
	v_mov_b32_e32 v110, v133
	v_mov_b32_e32 v111, v133
	v_mov_b32_e32 v112, 0
	v_mov_b32_e32 v113, v133
	v_mov_b32_e32 v114, v133
	v_mov_b32_e32 v115, v133
	v_mov_b32_e32 v116, 0
	v_mov_b32_e32 v117, v133
	v_mov_b32_e32 v118, v133
	v_mov_b32_e32 v119, v133
	v_mov_b32_e32 v120, 0
	v_mov_b32_e32 v121, v133
	v_mov_b32_e32 v122, v133
	v_mov_b32_e32 v123, v133
	v_mov_b32_e32 v124, 0
	v_mov_b32_e32 v125, v133
	v_mov_b32_e32 v126, v133
	v_mov_b32_e32 v127, v133
	s_waitcnt vmcnt(0) lgkmcnt(0)
	s_barrier
	v_readfirstlane_b32 s66, v140
	v_readfirstlane_b32 s67, v141
	s_and_b32 s70, s4, 0x8000
	s_xor_b32 s71, s70, 0x8000
	v_add3_u32 v143, v137, v142, s70
	v_add3_u32 v157, v139, v142, s70
	ds_read_b128 v[174:177], v143
	ds_read_b128 v[178:181], v143 offset:2048
	ds_read_b128 v[182:185], v143 offset:4096
	ds_read_b128 v[144:147], v143 offset:6144
	ds_read_b128 v[158:161], v157
	ds_read_b128 v[162:165], v157 offset:2048
	ds_read_b128 v[166:169], v157 offset:4096
	ds_read_b128 v[170:173], v157 offset:6144
	s_add_i32 s76, s66, s71
	s_add_i32 s77, s67, s71
	s_lshr_b32 s71, s23, 3
	s_and_b32 s71, s71, 31
	s_cmp_eq_u32 s71, 31
	s_cselect_b32 s71, 0, s71
	s_lshl_b32 s71, s71, 7
	s_add_i32 vcc_lo, s62, s71
	s_cmp_ge_u32 vcc_lo, 0xf80
	s_cselect_b32 vcc_hi, 0xf80, 0
	s_sub_i32 vcc_lo, vcc_lo, vcc_hi
	s_add_u32 s68, vcc_lo, s38
	s_addc_u32 s69, 0, s39
	s_add_i32 m0, s76, 0x0
	v_lshl_add_u64 v[242:243], v[128:129], 0, s[68:69]
	global_load_lds_dwordx4 v[242:243], off
	s_add_u32 s68, vcc_lo, s40
	s_addc_u32 s69, 0, s41
	s_add_i32 m0, s77, 0x0
	v_lshl_add_u64 v[242:243], v[130:131], 0, s[68:69]
	global_load_lds_dwordx4 v[242:243], off
	s_add_u32 s68, vcc_lo, s44
	s_addc_u32 s69, 0, s45
	s_add_i32 m0, s76, 0x2000
	v_lshl_add_u64 v[242:243], v[128:129], 0, s[68:69]
	global_load_lds_dwordx4 v[242:243], off
	s_add_u32 s68, vcc_lo, s48
	s_addc_u32 s69, 0, s49
	s_add_i32 m0, s77, 0x2000
	v_lshl_add_u64 v[242:243], v[130:131], 0, s[68:69]
	global_load_lds_dwordx4 v[242:243], off
	s_add_u32 s68, vcc_lo, s50
	s_addc_u32 s69, 0, s51
	s_add_i32 m0, s76, 0x4000
	v_lshl_add_u64 v[242:243], v[128:129], 0, s[68:69]
	global_load_lds_dwordx4 v[242:243], off
	s_add_u32 s68, vcc_lo, s54
	s_addc_u32 s69, 0, s55
	s_add_i32 m0, s77, 0x4000
	v_lshl_add_u64 v[242:243], v[130:131], 0, s[68:69]
	global_load_lds_dwordx4 v[242:243], off
	s_add_u32 s68, vcc_lo, s56
	s_addc_u32 s69, 0, s57
	s_add_i32 m0, s76, 0x6000
	v_lshl_add_u64 v[242:243], v[128:129], 0, s[68:69]
	global_load_lds_dwordx4 v[242:243], off
	s_add_u32 s68, vcc_lo, s58
	s_addc_u32 s69, 0, s59
	s_add_i32 m0, s77, 0x6000
	v_lshl_add_u64 v[242:243], v[130:131], 0, s[68:69]
	global_load_lds_dwordx4 v[242:243], off
.LBB0_496:
	s_and_b32 s70, s4, 0x8000
	s_add_i32 s4, s4, 0x8000
	v_add3_u32 v143, v137, v138, s70
	v_add3_u32 v157, v139, v142, s70
	v_add3_u32 v186, v139, v138, s70
	s_waitcnt lgkmcnt(3)
	v_mfma_f32_16x16x32_bf16 v[124:127], v[174:177], v[158:161], v[124:127]
	v_mfma_f32_16x16x32_bf16 v[96:99], v[178:181], v[158:161], v[96:99]
	v_mfma_f32_16x16x32_bf16 v[72:75], v[182:185], v[158:161], v[72:75]
	v_mfma_f32_16x16x32_bf16 v[48:51], v[144:147], v[158:161], v[48:51]
	ds_read_b128 v[158:161], v157 offset:16384
	ds_read_b128 v[148:151], v143
	s_waitcnt lgkmcnt(4)
	v_mfma_f32_16x16x32_bf16 v[120:123], v[174:177], v[162:165], v[120:123]
	v_mfma_f32_16x16x32_bf16 v[92:95], v[178:181], v[162:165], v[92:95]
	v_mfma_f32_16x16x32_bf16 v[68:71], v[182:185], v[162:165], v[68:71]
	v_mfma_f32_16x16x32_bf16 v[44:47], v[144:147], v[162:165], v[44:47]
	ds_read_b128 v[162:165], v157 offset:18432
	ds_read_b128 v[152:155], v143 offset:2048
	s_waitcnt lgkmcnt(5)
	v_mfma_f32_16x16x32_bf16 v[116:119], v[174:177], v[166:169], v[116:119]
	v_mfma_f32_16x16x32_bf16 v[88:91], v[178:181], v[166:169], v[88:91]
	v_mfma_f32_16x16x32_bf16 v[64:67], v[182:185], v[166:169], v[64:67]
	v_mfma_f32_16x16x32_bf16 v[40:43], v[144:147], v[166:169], v[40:43]
	ds_read_b128 v[166:169], v157 offset:20480
	ds_read_b128 v[244:247], v143 offset:4096
	s_waitcnt lgkmcnt(6)
	v_mfma_f32_16x16x32_bf16 v[112:115], v[174:177], v[170:173], v[112:115]
	v_mfma_f32_16x16x32_bf16 v[84:87], v[178:181], v[170:173], v[84:87]
	v_mfma_f32_16x16x32_bf16 v[60:63], v[182:185], v[170:173], v[60:63]
	v_mfma_f32_16x16x32_bf16 v[36:39], v[144:147], v[170:173], v[36:39]
	ds_read_b128 v[170:173], v157 offset:22528
	ds_read_b128 v[248:251], v143 offset:6144
	s_waitcnt lgkmcnt(7)
	v_mfma_f32_16x16x32_bf16 v[108:111], v[174:177], v[158:161], v[108:111]
	v_mfma_f32_16x16x32_bf16 v[80:83], v[178:181], v[158:161], v[80:83]
	v_mfma_f32_16x16x32_bf16 v[56:59], v[182:185], v[158:161], v[56:59]
	v_mfma_f32_16x16x32_bf16 v[32:35], v[144:147], v[158:161], v[32:35]
	ds_read_b128 v[158:161], v186
	s_waitcnt lgkmcnt(6)
	v_mfma_f32_16x16x32_bf16 v[28:31], v[174:177], v[162:165], v[28:31]
	v_mfma_f32_16x16x32_bf16 v[16:19], v[178:181], v[162:165], v[16:19]
	v_mfma_f32_16x16x32_bf16 v[8:11], v[182:185], v[162:165], v[8:11]
	v_mfma_f32_16x16x32_bf16 v[0:3], v[144:147], v[162:165], v[0:3]
	ds_read_b128 v[162:165], v186 offset:2048
	s_waitcnt lgkmcnt(5)
	v_mfma_f32_16x16x32_bf16 v[104:107], v[174:177], v[166:169], v[104:107]
	v_mfma_f32_16x16x32_bf16 v[76:79], v[178:181], v[166:169], v[76:79]
	v_mfma_f32_16x16x32_bf16 v[52:55], v[182:185], v[166:169], v[52:55]
	v_mfma_f32_16x16x32_bf16 v[100:103], v[144:147], v[166:169], v[100:103]
	ds_read_b128 v[166:169], v186 offset:4096
	s_waitcnt lgkmcnt(4)
	v_mfma_f32_16x16x32_bf16 v[24:27], v[174:177], v[170:173], v[24:27]
	v_mfma_f32_16x16x32_bf16 v[12:15], v[178:181], v[170:173], v[12:15]
	v_mfma_f32_16x16x32_bf16 v[4:7], v[182:185], v[170:173], v[4:7]
	v_mfma_f32_16x16x32_bf16 v[20:23], v[144:147], v[170:173], v[20:23]
	ds_read_b128 v[170:173], v186 offset:6144
	s_waitcnt lgkmcnt(3)
	v_mfma_f32_16x16x32_bf16 v[124:127], v[148:151], v[158:161], v[124:127]
	v_mfma_f32_16x16x32_bf16 v[96:99], v[152:155], v[158:161], v[96:99]
	v_mfma_f32_16x16x32_bf16 v[72:75], v[244:247], v[158:161], v[72:75]
	v_mfma_f32_16x16x32_bf16 v[48:51], v[248:251], v[158:161], v[48:51]
	ds_read_b128 v[158:161], v186 offset:16384
	s_waitcnt lgkmcnt(3)
	v_mfma_f32_16x16x32_bf16 v[120:123], v[148:151], v[162:165], v[120:123]
	v_mfma_f32_16x16x32_bf16 v[92:95], v[152:155], v[162:165], v[92:95]
	v_mfma_f32_16x16x32_bf16 v[68:71], v[244:247], v[162:165], v[68:71]
	v_mfma_f32_16x16x32_bf16 v[44:47], v[248:251], v[162:165], v[44:47]
	ds_read_b128 v[162:165], v186 offset:18432
	s_waitcnt lgkmcnt(3)
	v_mfma_f32_16x16x32_bf16 v[116:119], v[148:151], v[166:169], v[116:119]
	v_mfma_f32_16x16x32_bf16 v[88:91], v[152:155], v[166:169], v[88:91]
	v_mfma_f32_16x16x32_bf16 v[64:67], v[244:247], v[166:169], v[64:67]
	v_mfma_f32_16x16x32_bf16 v[40:43], v[248:251], v[166:169], v[40:43]
	ds_read_b128 v[166:169], v186 offset:20480
	s_waitcnt lgkmcnt(3)
	v_mfma_f32_16x16x32_bf16 v[112:115], v[148:151], v[170:173], v[112:115]
	v_mfma_f32_16x16x32_bf16 v[84:87], v[152:155], v[170:173], v[84:87]
	v_mfma_f32_16x16x32_bf16 v[60:63], v[244:247], v[170:173], v[60:63]
	v_mfma_f32_16x16x32_bf16 v[36:39], v[248:251], v[170:173], v[36:39]
	ds_read_b128 v[170:173], v186 offset:22528
	s_waitcnt lgkmcnt(3)
	v_mfma_f32_16x16x32_bf16 v[108:111], v[148:151], v[158:161], v[108:111]
	v_mfma_f32_16x16x32_bf16 v[80:83], v[152:155], v[158:161], v[80:83]
	v_mfma_f32_16x16x32_bf16 v[56:59], v[244:247], v[158:161], v[56:59]
	v_mfma_f32_16x16x32_bf16 v[32:35], v[248:251], v[158:161], v[32:35]
	s_add_u32 s62, s62, 0x80
	s_addc_u32 s63, s63, 0
	s_cmpk_eq_i32 s62, 0xf80
	s_waitcnt vmcnt(0) lgkmcnt(0)
	s_barrier
	s_cbranch_scc1 .Lgemm_496_exit
	s_xor_b32 s71, s70, 0x8000
	v_add3_u32 v143, v137, v142, s71
	v_add3_u32 v157, v139, v142, s71
	ds_read_b128 v[174:177], v143
	ds_read_b128 v[178:181], v143 offset:2048
	ds_read_b128 v[182:185], v143 offset:4096
	ds_read_b128 v[144:147], v143 offset:6144
	ds_read_b128 v[158:161], v157
	s_add_i32 s76, s66, s70
	s_add_i32 s77, s67, s70
	s_lshr_b32 s71, s23, 3
	s_and_b32 s71, s71, 31
	s_cmp_eq_u32 s71, 31
	s_cselect_b32 s71, 0, s71
	s_lshl_b32 s71, s71, 7
	s_add_i32 vcc_lo, s62, s71
	s_cmp_ge_u32 vcc_lo, 0xf80
	s_cselect_b32 vcc_hi, 0xf80, 0
	s_sub_i32 vcc_lo, vcc_lo, vcc_hi
	s_add_u32 s68, vcc_lo, s38
	s_addc_u32 s69, 0, s39
	s_add_i32 m0, s76, 0x0
	v_lshl_add_u64 v[242:243], v[128:129], 0, s[68:69]
	global_load_lds_dwordx4 v[242:243], off
	s_add_u32 s68, vcc_lo, s40
	s_addc_u32 s69, 0, s41
	s_add_i32 m0, s77, 0x0
	v_lshl_add_u64 v[242:243], v[130:131], 0, s[68:69]
	global_load_lds_dwordx4 v[242:243], off
	v_mfma_f32_16x16x32_bf16 v[28:31], v[148:151], v[162:165], v[28:31]
	v_mfma_f32_16x16x32_bf16 v[16:19], v[152:155], v[162:165], v[16:19]
	v_mfma_f32_16x16x32_bf16 v[8:11], v[244:247], v[162:165], v[8:11]
	v_mfma_f32_16x16x32_bf16 v[0:3], v[248:251], v[162:165], v[0:3]
	ds_read_b128 v[162:165], v157 offset:2048
	s_add_u32 s68, vcc_lo, s44
	s_addc_u32 s69, 0, s45
	s_add_i32 m0, s76, 0x2000
	v_lshl_add_u64 v[242:243], v[128:129], 0, s[68:69]
	global_load_lds_dwordx4 v[242:243], off
	s_add_u32 s68, vcc_lo, s48
	s_addc_u32 s69, 0, s49
	s_add_i32 m0, s77, 0x2000
	v_lshl_add_u64 v[242:243], v[130:131], 0, s[68:69]
	global_load_lds_dwordx4 v[242:243], off
	v_mfma_f32_16x16x32_bf16 v[104:107], v[148:151], v[166:169], v[104:107]
	v_mfma_f32_16x16x32_bf16 v[76:79], v[152:155], v[166:169], v[76:79]
	v_mfma_f32_16x16x32_bf16 v[52:55], v[244:247], v[166:169], v[52:55]
	v_mfma_f32_16x16x32_bf16 v[100:103], v[248:251], v[166:169], v[100:103]
	ds_read_b128 v[166:169], v157 offset:4096
	s_add_u32 s68, vcc_lo, s50
	s_addc_u32 s69, 0, s51
	s_add_i32 m0, s76, 0x4000
	v_lshl_add_u64 v[242:243], v[128:129], 0, s[68:69]
	global_load_lds_dwordx4 v[242:243], off
	s_add_u32 s68, vcc_lo, s54
	s_addc_u32 s69, 0, s55
	s_add_i32 m0, s77, 0x4000
	v_lshl_add_u64 v[242:243], v[130:131], 0, s[68:69]
	global_load_lds_dwordx4 v[242:243], off
	v_mfma_f32_16x16x32_bf16 v[24:27], v[148:151], v[170:173], v[24:27]
	v_mfma_f32_16x16x32_bf16 v[12:15], v[152:155], v[170:173], v[12:15]
	v_mfma_f32_16x16x32_bf16 v[4:7], v[244:247], v[170:173], v[4:7]
	v_mfma_f32_16x16x32_bf16 v[20:23], v[248:251], v[170:173], v[20:23]
	ds_read_b128 v[170:173], v157 offset:6144
	s_add_u32 s68, vcc_lo, s56
	s_addc_u32 s69, 0, s57
	s_add_i32 m0, s76, 0x6000
	v_lshl_add_u64 v[242:243], v[128:129], 0, s[68:69]
	global_load_lds_dwordx4 v[242:243], off
	s_add_u32 s68, vcc_lo, s58
	s_addc_u32 s69, 0, s59
	s_add_i32 m0, s77, 0x6000
	v_lshl_add_u64 v[242:243], v[130:131], 0, s[68:69]
	global_load_lds_dwordx4 v[242:243], off
	s_branch .LBB0_496

.LBB0_620:
	s_ashr_i32 s61, s85, 6
	v_mov_b32_e32 v10, v156
	s_and_b32 s62, s84, 63
	s_and_b32 s63, s85, 63
	s_lshl_b32 s58, s61, 8
	s_lshl_b32 s0, s62, 20
	v_ashrrev_i32_e32 v0, 3, v10
	s_ashr_i32 s59, s58, 31
	s_lshl_b32 s4, s63, 20
	v_xor_b32_e32 v6, v0, v10
	v_ashrrev_i32_e32 v1, 31, v0
	s_add_u32 s4, s24, s4
	v_lshlrev_b64 v[2:3], 12, v[0:1]
	v_lshlrev_b32_e32 v1, 4, v6
	s_addc_u32 s5, s25, 0
	s_lshl_b64 s[64:65], s[58:59], 12
	v_and_b32_e32 v132, 0x70, v1
	v_lshlrev_b32_e32 v1, 4, v10
	s_add_u32 s66, s16, s64
	v_add_u32_e32 v141, 0, v1
	s_addc_u32 s67, s17, s65
	v_lshl_add_u64 v[4:5], s[4:5], 0, v[2:3]
	v_add_u32_e32 v142, s8, v1
	v_readfirstlane_b32 s4, v141
	v_lshl_add_u64 v[4:5], v[4:5], 0, v[132:133]
	v_lshl_add_u64 v[6:7], s[66:67], 0, v[2:3]
	s_mov_b32 m0, s4
	v_readfirstlane_b32 s4, v142
	v_add_u32_e32 v1, 0x2000, v141
	v_lshl_add_u64 v[6:7], v[6:7], 0, v[132:133]
	s_barrier
	global_load_lds_dwordx4 v[4:5], off
	s_mov_b32 m0, s4
	v_readfirstlane_b32 s4, v1
	v_add_u32_e32 v1, 0x2000, v142
	global_load_lds_dwordx4 v[6:7], off
	v_lshl_add_u64 v[8:9], v[4:5], 0, s[6:7]
	s_mov_b32 m0, s4
	v_readfirstlane_b32 s4, v1
	v_add_u32_e32 v1, 0x4000, v141
	global_load_lds_dwordx4 v[8:9], off
	v_lshl_add_u64 v[8:9], v[6:7], 0, s[6:7]
	s_mov_b32 m0, s4
	v_readfirstlane_b32 s4, v1
	v_add_u32_e32 v1, 0x4000, v142
	global_load_lds_dwordx4 v[8:9], off
	v_lshl_add_u64 v[8:9], v[4:5], 0, s[18:19]
	s_mov_b32 m0, s4
	v_readfirstlane_b32 s4, v1
	v_add_u32_e32 v1, 0x6000, v141
	global_load_lds_dwordx4 v[8:9], off
	v_lshl_add_u64 v[8:9], v[6:7], 0, s[18:19]
	s_mov_b32 m0, s4
	v_readfirstlane_b32 s4, v1
	v_add_u32_e32 v1, 0x6000, v142
	global_load_lds_dwordx4 v[8:9], off
	v_lshl_add_u64 v[4:5], v[4:5], 0, s[26:27]
	s_mov_b32 m0, s4
	v_readfirstlane_b32 s4, v1
	global_load_lds_dwordx4 v[4:5], off
	v_lshl_add_u64 v[4:5], v[6:7], 0, s[26:27]
	s_mov_b32 m0, s4
	v_ashrrev_i32_e32 v1, 1, v10
	global_load_lds_dwordx4 v[4:5], off
	v_and_b32_e32 v135, 15, v10
	v_and_b32_e32 v136, 0xffffffc0, v1
	v_lshrrev_b32_e32 v11, 4, v10
	v_or_b32_e32 v1, v136, v135
	v_and_b32_e32 v6, 7, v10
	v_bfe_u32 v134, v10, 6, 1
	v_bfe_u32 v132, v10, 4, 2
	v_lshl_add_u32 v137, v1, 7, 0
	v_bitop3_b32 v1, v11, v6, 3 bitop3:0x6c
	v_lshlrev_b32_e32 v4, 13, v134
	v_lshlrev_b32_e32 v5, 7, v135
	v_lshlrev_b32_e32 v140, 4, v1
	v_bitop3_b32 v1, v132, v6, 4 bitop3:0x36
	v_bitop3_b32 v0, v0, 7, v10 bitop3:0x48
	s_waitcnt vmcnt(0)
	v_add3_u32 v139, s8, v4, v5
	v_lshlrev_b32_e32 v138, 4, v1
	v_lshl_add_u64 v[4:5], s[0:1], 0, v[2:3]
	v_lshlrev_b32_e32 v6, 4, v0
	v_lshl_add_u64 v[0:1], v[2:3], 0, s[64:65]
	v_or_b32_e32 v4, v4, v6
	v_or_b32_e32 v0, v0, v6
	v_lshl_add_u64 v[128:129], s[72:73], 0, v[4:5]
	v_lshl_add_u64 v[130:131], s[72:73], 0, v[0:1]
	s_mov_b64 s[4:5], 0
	s_mov_b32 s60, s1
	v_mov_b32_e32 v20, 0
	v_mov_b32_e32 v21, v133
	v_mov_b32_e32 v22, v133
	v_mov_b32_e32 v23, v133
	v_mov_b32_e32 v56, 0
	v_mov_b32_e32 v57, v133
	v_mov_b32_e32 v58, v133
	v_mov_b32_e32 v59, v133
	v_mov_b32_e32 v0, 0
	v_mov_b32_e32 v1, v133
	v_mov_b32_e32 v2, v133
	v_mov_b32_e32 v3, v133
	v_mov_b32_e32 v32, 0
	v_mov_b32_e32 v33, v133
	v_mov_b32_e32 v34, v133
	v_mov_b32_e32 v35, v133
	v_mov_b32_e32 v64, 0
	v_mov_b32_e32 v65, v133
	v_mov_b32_e32 v66, v133
	v_mov_b32_e32 v67, v133
	v_mov_b32_e32 v68, 0
	v_mov_b32_e32 v69, v133
	v_mov_b32_e32 v70, v133
	v_mov_b32_e32 v71, v133
	v_mov_b32_e32 v72, 0
	v_mov_b32_e32 v73, v133
	v_mov_b32_e32 v74, v133
	v_mov_b32_e32 v75, v133
	v_mov_b32_e32 v76, 0
	v_mov_b32_e32 v77, v133
	v_mov_b32_e32 v78, v133
	v_mov_b32_e32 v79, v133
	v_mov_b32_e32 v4, 0
	v_mov_b32_e32 v5, v133
	v_mov_b32_e32 v6, v133
	v_mov_b32_e32 v7, v133
	v_mov_b32_e32 v36, 0
	v_mov_b32_e32 v37, v133
	v_mov_b32_e32 v38, v133
	v_mov_b32_e32 v39, v133
	v_mov_b32_e32 v8, 0
	v_mov_b32_e32 v9, v133
	v_mov_b32_e32 v10, v133
	v_mov_b32_e32 v11, v133
	v_mov_b32_e32 v40, 0
	v_mov_b32_e32 v41, v133
	v_mov_b32_e32 v42, v133
	v_mov_b32_e32 v43, v133
	v_mov_b32_e32 v80, 0
	v_mov_b32_e32 v81, v133
	v_mov_b32_e32 v82, v133
	v_mov_b32_e32 v83, v133
	v_mov_b32_e32 v84, 0
	v_mov_b32_e32 v85, v133
	v_mov_b32_e32 v86, v133
	v_mov_b32_e32 v87, v133
	v_mov_b32_e32 v88, 0
	v_mov_b32_e32 v89, v133
	v_mov_b32_e32 v90, v133
	v_mov_b32_e32 v91, v133
	v_mov_b32_e32 v92, 0
	v_mov_b32_e32 v93, v133
	v_mov_b32_e32 v94, v133
	v_mov_b32_e32 v95, v133
	v_mov_b32_e32 v12, 0
	v_mov_b32_e32 v13, v133
	v_mov_b32_e32 v14, v133
	v_mov_b32_e32 v15, v133
	v_mov_b32_e32 v44, 0
	v_mov_b32_e32 v45, v133
	v_mov_b32_e32 v46, v133
	v_mov_b32_e32 v47, v133
	v_mov_b32_e32 v16, 0
	v_mov_b32_e32 v17, v133
	v_mov_b32_e32 v18, v133
	v_mov_b32_e32 v19, v133
	v_mov_b32_e32 v48, 0
	v_mov_b32_e32 v49, v133
	v_mov_b32_e32 v50, v133
	v_mov_b32_e32 v51, v133
	v_mov_b32_e32 v96, 0
	v_mov_b32_e32 v97, v133
	v_mov_b32_e32 v98, v133
	v_mov_b32_e32 v99, v133
	v_mov_b32_e32 v100, 0
	v_mov_b32_e32 v101, v133
	v_mov_b32_e32 v102, v133
	v_mov_b32_e32 v103, v133
	v_mov_b32_e32 v104, 0
	v_mov_b32_e32 v105, v133
	v_mov_b32_e32 v106, v133
	v_mov_b32_e32 v107, v133
	v_mov_b32_e32 v108, 0
	v_mov_b32_e32 v109, v133
	v_mov_b32_e32 v110, v133
	v_mov_b32_e32 v111, v133
	v_mov_b32_e32 v24, 0
	v_mov_b32_e32 v25, v133
	v_mov_b32_e32 v26, v133
	v_mov_b32_e32 v27, v133
	v_mov_b32_e32 v52, 0
	v_mov_b32_e32 v53, v133
	v_mov_b32_e32 v54, v133
	v_mov_b32_e32 v55, v133
	v_mov_b32_e32 v28, 0
	v_mov_b32_e32 v29, v133
	v_mov_b32_e32 v30, v133
	v_mov_b32_e32 v31, v133
	v_mov_b32_e32 v60, 0
	v_mov_b32_e32 v61, v133
	v_mov_b32_e32 v62, v133
	v_mov_b32_e32 v63, v133
	v_mov_b32_e32 v112, 0
	v_mov_b32_e32 v113, v133
	v_mov_b32_e32 v114, v133
	v_mov_b32_e32 v115, v133
	v_mov_b32_e32 v116, 0
	v_mov_b32_e32 v117, v133
	v_mov_b32_e32 v118, v133
	v_mov_b32_e32 v119, v133
	v_mov_b32_e32 v120, 0
	v_mov_b32_e32 v121, v133
	v_mov_b32_e32 v122, v133
	v_mov_b32_e32 v123, v133
	v_mov_b32_e32 v124, 0
	v_mov_b32_e32 v125, v133
	v_mov_b32_e32 v126, v133
	v_mov_b32_e32 v127, v133
	s_waitcnt vmcnt(0) lgkmcnt(0)
	s_barrier
	v_readfirstlane_b32 s64, v141
	v_readfirstlane_b32 s65, v142
	s_and_b32 s68, s60, 0x8000
	s_xor_b32 s69, s68, 0x8000
	v_add3_u32 v143, v137, v140, s68
	v_add3_u32 v157, v139, v140, s68
	ds_read_b128 v[174:177], v143
	ds_read_b128 v[178:181], v143 offset:2048
	ds_read_b128 v[182:185], v143 offset:4096
	ds_read_b128 v[144:147], v143 offset:6144
	ds_read_b128 v[158:161], v157
	ds_read_b128 v[162:165], v157 offset:2048
	ds_read_b128 v[166:169], v157 offset:4096
	ds_read_b128 v[170:173], v157 offset:6144
	s_add_i32 s70, s64, s69
	s_add_i32 s71, s65, s69
	s_lshr_b32 s69, s23, 3
	s_and_b32 s69, s69, 7
	s_lshl_b32 s69, s69, 9
	s_add_i32 vcc_lo, s4, s69
	s_cmp_ge_u32 vcc_lo, 0xf80
	s_cselect_b32 vcc_hi, 0xf80, 0
	s_sub_i32 vcc_lo, vcc_lo, vcc_hi
	s_add_u32 s66, vcc_lo, s36
	s_addc_u32 s67, 0, s37
	s_add_i32 m0, s70, 0x0
	v_lshl_add_u64 v[242:243], v[128:129], 0, s[66:67]
	global_load_lds_dwordx4 v[242:243], off
	s_add_u32 s66, vcc_lo, s38
	s_addc_u32 s67, 0, s39
	s_add_i32 m0, s71, 0x0
	v_lshl_add_u64 v[242:243], v[130:131], 0, s[66:67]
	global_load_lds_dwordx4 v[242:243], off
	s_add_u32 s66, vcc_lo, s40
	s_addc_u32 s67, 0, s41
	s_add_i32 m0, s70, 0x2000
	v_lshl_add_u64 v[242:243], v[128:129], 0, s[66:67]
	global_load_lds_dwordx4 v[242:243], off
	s_add_u32 s66, vcc_lo, s42
	s_addc_u32 s67, 0, s43
	s_add_i32 m0, s71, 0x2000
	v_lshl_add_u64 v[242:243], v[130:131], 0, s[66:67]
	global_load_lds_dwordx4 v[242:243], off
	s_add_u32 s66, vcc_lo, s44
	s_addc_u32 s67, 0, s45
	s_add_i32 m0, s70, 0x4000
	v_lshl_add_u64 v[242:243], v[128:129], 0, s[66:67]
	global_load_lds_dwordx4 v[242:243], off
	s_add_u32 s66, vcc_lo, s48
	s_addc_u32 s67, 0, s49
	s_add_i32 m0, s71, 0x4000
	v_lshl_add_u64 v[242:243], v[130:131], 0, s[66:67]
	global_load_lds_dwordx4 v[242:243], off
	s_add_u32 s66, vcc_lo, s50
	s_addc_u32 s67, 0, s51
	s_add_i32 m0, s70, 0x6000
	v_lshl_add_u64 v[242:243], v[128:129], 0, s[66:67]
	global_load_lds_dwordx4 v[242:243], off
	s_add_u32 s66, vcc_lo, s54
	s_addc_u32 s67, 0, s55
	s_add_i32 m0, s71, 0x6000
	v_lshl_add_u64 v[242:243], v[130:131], 0, s[66:67]
	global_load_lds_dwordx4 v[242:243], off
.LBB0_621:
	s_and_b32 s68, s60, 0x8000
	s_add_i32 s60, s60, 0x8000
	v_add3_u32 v143, v137, v138, s68
	v_add3_u32 v157, v139, v140, s68
	v_add3_u32 v186, v139, v138, s68
	s_waitcnt lgkmcnt(3)
	v_mfma_f32_16x16x32_bf16 v[124:127], v[174:177], v[158:161], v[124:127]
	v_mfma_f32_16x16x32_bf16 v[108:111], v[178:181], v[158:161], v[108:111]
	v_mfma_f32_16x16x32_bf16 v[92:95], v[182:185], v[158:161], v[92:95]
	v_mfma_f32_16x16x32_bf16 v[76:79], v[144:147], v[158:161], v[76:79]
	ds_read_b128 v[158:161], v157 offset:16384
	ds_read_b128 v[148:151], v143
	s_waitcnt lgkmcnt(4)
	v_mfma_f32_16x16x32_bf16 v[120:123], v[174:177], v[162:165], v[120:123]
	v_mfma_f32_16x16x32_bf16 v[104:107], v[178:181], v[162:165], v[104:107]
	v_mfma_f32_16x16x32_bf16 v[88:91], v[182:185], v[162:165], v[88:91]
	v_mfma_f32_16x16x32_bf16 v[72:75], v[144:147], v[162:165], v[72:75]
	ds_read_b128 v[162:165], v157 offset:18432
	ds_read_b128 v[152:155], v143 offset:2048
	s_waitcnt lgkmcnt(5)
	v_mfma_f32_16x16x32_bf16 v[116:119], v[174:177], v[166:169], v[116:119]
	v_mfma_f32_16x16x32_bf16 v[100:103], v[178:181], v[166:169], v[100:103]
	v_mfma_f32_16x16x32_bf16 v[84:87], v[182:185], v[166:169], v[84:87]
	v_mfma_f32_16x16x32_bf16 v[68:71], v[144:147], v[166:169], v[68:71]
	ds_read_b128 v[166:169], v157 offset:20480
	ds_read_b128 v[244:247], v143 offset:4096
	s_waitcnt lgkmcnt(6)
	v_mfma_f32_16x16x32_bf16 v[112:115], v[174:177], v[170:173], v[112:115]
	v_mfma_f32_16x16x32_bf16 v[96:99], v[178:181], v[170:173], v[96:99]
	v_mfma_f32_16x16x32_bf16 v[80:83], v[182:185], v[170:173], v[80:83]
	v_mfma_f32_16x16x32_bf16 v[64:67], v[144:147], v[170:173], v[64:67]
	ds_read_b128 v[170:173], v157 offset:22528
	ds_read_b128 v[248:251], v143 offset:6144
	s_waitcnt lgkmcnt(7)
	v_mfma_f32_16x16x32_bf16 v[60:63], v[174:177], v[158:161], v[60:63]
	v_mfma_f32_16x16x32_bf16 v[48:51], v[178:181], v[158:161], v[48:51]
	v_mfma_f32_16x16x32_bf16 v[40:43], v[182:185], v[158:161], v[40:43]
	v_mfma_f32_16x16x32_bf16 v[32:35], v[144:147], v[158:161], v[32:35]
	ds_read_b128 v[158:161], v186
	s_waitcnt lgkmcnt(6)
	v_mfma_f32_16x16x32_bf16 v[28:31], v[174:177], v[162:165], v[28:31]
	v_mfma_f32_16x16x32_bf16 v[16:19], v[178:181], v[162:165], v[16:19]
	v_mfma_f32_16x16x32_bf16 v[8:11], v[182:185], v[162:165], v[8:11]
	v_mfma_f32_16x16x32_bf16 v[0:3], v[144:147], v[162:165], v[0:3]
	ds_read_b128 v[162:165], v186 offset:2048
	s_waitcnt lgkmcnt(5)
	v_mfma_f32_16x16x32_bf16 v[52:55], v[174:177], v[166:169], v[52:55]
	v_mfma_f32_16x16x32_bf16 v[44:47], v[178:181], v[166:169], v[44:47]
	v_mfma_f32_16x16x32_bf16 v[36:39], v[182:185], v[166:169], v[36:39]
	v_mfma_f32_16x16x32_bf16 v[56:59], v[144:147], v[166:169], v[56:59]
	ds_read_b128 v[166:169], v186 offset:4096
	s_waitcnt lgkmcnt(4)
	v_mfma_f32_16x16x32_bf16 v[24:27], v[174:177], v[170:173], v[24:27]
	v_mfma_f32_16x16x32_bf16 v[12:15], v[178:181], v[170:173], v[12:15]
	v_mfma_f32_16x16x32_bf16 v[4:7], v[182:185], v[170:173], v[4:7]
	v_mfma_f32_16x16x32_bf16 v[20:23], v[144:147], v[170:173], v[20:23]
	ds_read_b128 v[170:173], v186 offset:6144
	s_waitcnt lgkmcnt(3)
	v_mfma_f32_16x16x32_bf16 v[124:127], v[148:151], v[158:161], v[124:127]
	v_mfma_f32_16x16x32_bf16 v[108:111], v[152:155], v[158:161], v[108:111]
	v_mfma_f32_16x16x32_bf16 v[92:95], v[244:247], v[158:161], v[92:95]
	v_mfma_f32_16x16x32_bf16 v[76:79], v[248:251], v[158:161], v[76:79]
	ds_read_b128 v[158:161], v186 offset:16384
	s_waitcnt lgkmcnt(3)
	v_mfma_f32_16x16x32_bf16 v[120:123], v[148:151], v[162:165], v[120:123]
	v_mfma_f32_16x16x32_bf16 v[104:107], v[152:155], v[162:165], v[104:107]
	v_mfma_f32_16x16x32_bf16 v[88:91], v[244:247], v[162:165], v[88:91]
	v_mfma_f32_16x16x32_bf16 v[72:75], v[248:251], v[162:165], v[72:75]
	ds_read_b128 v[162:165], v186 offset:18432
	s_waitcnt lgkmcnt(3)
	v_mfma_f32_16x16x32_bf16 v[116:119], v[148:151], v[166:169], v[116:119]
	v_mfma_f32_16x16x32_bf16 v[100:103], v[152:155], v[166:169], v[100:103]
	v_mfma_f32_16x16x32_bf16 v[84:87], v[244:247], v[166:169], v[84:87]
	v_mfma_f32_16x16x32_bf16 v[68:71], v[248:251], v[166:169], v[68:71]
	ds_read_b128 v[166:169], v186 offset:20480
	s_waitcnt lgkmcnt(3)
	v_mfma_f32_16x16x32_bf16 v[112:115], v[148:151], v[170:173], v[112:115]
	v_mfma_f32_16x16x32_bf16 v[96:99], v[152:155], v[170:173], v[96:99]
	v_mfma_f32_16x16x32_bf16 v[80:83], v[244:247], v[170:173], v[80:83]
	v_mfma_f32_16x16x32_bf16 v[64:67], v[248:251], v[170:173], v[64:67]
	ds_read_b128 v[170:173], v186 offset:22528
	s_waitcnt lgkmcnt(3)
	v_mfma_f32_16x16x32_bf16 v[60:63], v[148:151], v[158:161], v[60:63]
	v_mfma_f32_16x16x32_bf16 v[48:51], v[152:155], v[158:161], v[48:51]
	v_mfma_f32_16x16x32_bf16 v[40:43], v[244:247], v[158:161], v[40:43]
	v_mfma_f32_16x16x32_bf16 v[32:35], v[248:251], v[158:161], v[32:35]
	s_add_u32 s4, s4, 0x80
	s_addc_u32 s5, s5, 0
	s_cmpk_eq_i32 s4, 0xf80
	s_waitcnt vmcnt(0) lgkmcnt(0)
	s_barrier
	s_cbranch_scc1 .Lgemm_621_exit
	s_xor_b32 s69, s68, 0x8000
	v_add3_u32 v143, v137, v140, s69
	v_add3_u32 v157, v139, v140, s69
	ds_read_b128 v[174:177], v143
	ds_read_b128 v[178:181], v143 offset:2048
	ds_read_b128 v[182:185], v143 offset:4096
	ds_read_b128 v[144:147], v143 offset:6144
	ds_read_b128 v[158:161], v157
	s_add_i32 s70, s64, s68
	s_add_i32 s71, s65, s68
	s_lshr_b32 s69, s23, 3
	s_and_b32 s69, s69, 7
	s_lshl_b32 s69, s69, 9
	s_add_i32 vcc_lo, s4, s69
	s_cmp_ge_u32 vcc_lo, 0xf80
	s_cselect_b32 vcc_hi, 0xf80, 0
	s_sub_i32 vcc_lo, vcc_lo, vcc_hi
	s_add_u32 s66, vcc_lo, s36
	s_addc_u32 s67, 0, s37
	s_add_i32 m0, s70, 0x0
	v_lshl_add_u64 v[242:243], v[128:129], 0, s[66:67]
	global_load_lds_dwordx4 v[242:243], off
	s_add_u32 s66, vcc_lo, s38
	s_addc_u32 s67, 0, s39
	s_add_i32 m0, s71, 0x0
	v_lshl_add_u64 v[242:243], v[130:131], 0, s[66:67]
	global_load_lds_dwordx4 v[242:243], off
	v_mfma_f32_16x16x32_bf16 v[28:31], v[148:151], v[162:165], v[28:31]
	v_mfma_f32_16x16x32_bf16 v[16:19], v[152:155], v[162:165], v[16:19]
	v_mfma_f32_16x16x32_bf16 v[8:11], v[244:247], v[162:165], v[8:11]
	v_mfma_f32_16x16x32_bf16 v[0:3], v[248:251], v[162:165], v[0:3]
	ds_read_b128 v[162:165], v157 offset:2048
	s_add_u32 s66, vcc_lo, s40
	s_addc_u32 s67, 0, s41
	s_add_i32 m0, s70, 0x2000
	v_lshl_add_u64 v[242:243], v[128:129], 0, s[66:67]
	global_load_lds_dwordx4 v[242:243], off
	s_add_u32 s66, vcc_lo, s42
	s_addc_u32 s67, 0, s43
	s_add_i32 m0, s71, 0x2000
	v_lshl_add_u64 v[242:243], v[130:131], 0, s[66:67]
	global_load_lds_dwordx4 v[242:243], off
	v_mfma_f32_16x16x32_bf16 v[52:55], v[148:151], v[166:169], v[52:55]
	v_mfma_f32_16x16x32_bf16 v[44:47], v[152:155], v[166:169], v[44:47]
	v_mfma_f32_16x16x32_bf16 v[36:39], v[244:247], v[166:169], v[36:39]
	v_mfma_f32_16x16x32_bf16 v[56:59], v[248:251], v[166:169], v[56:59]
	ds_read_b128 v[166:169], v157 offset:4096
	s_add_u32 s66, vcc_lo, s44
	s_addc_u32 s67, 0, s45
	s_add_i32 m0, s70, 0x4000
	v_lshl_add_u64 v[242:243], v[128:129], 0, s[66:67]
	global_load_lds_dwordx4 v[242:243], off
	s_add_u32 s66, vcc_lo, s48
	s_addc_u32 s67, 0, s49
	s_add_i32 m0, s71, 0x4000
	v_lshl_add_u64 v[242:243], v[130:131], 0, s[66:67]
	global_load_lds_dwordx4 v[242:243], off
	v_mfma_f32_16x16x32_bf16 v[24:27], v[148:151], v[170:173], v[24:27]
	v_mfma_f32_16x16x32_bf16 v[12:15], v[152:155], v[170:173], v[12:15]
	v_mfma_f32_16x16x32_bf16 v[4:7], v[244:247], v[170:173], v[4:7]
	v_mfma_f32_16x16x32_bf16 v[20:23], v[248:251], v[170:173], v[20:23]
	ds_read_b128 v[170:173], v157 offset:6144
	s_add_u32 s66, vcc_lo, s50
	s_addc_u32 s67, 0, s51
	s_add_i32 m0, s70, 0x6000
	v_lshl_add_u64 v[242:243], v[128:129], 0, s[66:67]
	global_load_lds_dwordx4 v[242:243], off
	s_add_u32 s66, vcc_lo, s54
	s_addc_u32 s67, 0, s55
	s_add_i32 m0, s71, 0x6000
	v_lshl_add_u64 v[242:243], v[130:131], 0, s[66:67]
	global_load_lds_dwordx4 v[242:243], off
	s_branch .LBB0_621

.LBB0_697:
	s_ashr_i32 s55, s54, 6
	v_mov_b32_e32 v10, v156
	s_and_b32 s2, s33, 63
	s_and_b32 s56, s54, 63
	s_lshl_b32 s50, s55, 8
	s_lshl_b32 s2, s2, 20
	v_ashrrev_i32_e32 v0, 3, v10
	s_ashr_i32 s51, s50, 31
	s_lshl_b32 s52, s56, 20
	v_xor_b32_e32 v6, v0, v10
	v_ashrrev_i32_e32 v1, 31, v0
	s_add_u32 s52, s10, s52
	v_lshlrev_b64 v[2:3], 12, v[0:1]
	v_lshlrev_b32_e32 v1, 4, v6
	s_addc_u32 s53, s11, 0
	s_lshl_b64 s[58:59], s[50:51], 12
	v_and_b32_e32 v128, 0x70, v1
	v_lshlrev_b32_e32 v1, 4, v10
	s_add_u32 s60, s12, s58
	v_add_u32_e32 v141, 0, v1
	s_addc_u32 s61, s13, s59
	v_lshl_add_u64 v[4:5], s[52:53], 0, v[2:3]
	v_add_u32_e32 v142, s8, v1
	v_readfirstlane_b32 s52, v141
	v_lshl_add_u64 v[4:5], v[4:5], 0, v[128:129]
	v_lshl_add_u64 v[6:7], s[60:61], 0, v[2:3]
	s_mov_b32 m0, s52
	v_readfirstlane_b32 s52, v142
	v_add_u32_e32 v1, 0x2000, v141
	v_lshl_add_u64 v[6:7], v[6:7], 0, v[128:129]
	s_barrier
	global_load_lds_dwordx4 v[4:5], off
	s_mov_b32 m0, s52
	v_readfirstlane_b32 s52, v1
	v_add_u32_e32 v1, 0x2000, v142
	global_load_lds_dwordx4 v[6:7], off
	v_lshl_add_u64 v[8:9], v[4:5], 0, s[4:5]
	s_mov_b32 m0, s52
	v_readfirstlane_b32 s52, v1
	v_add_u32_e32 v1, 0x4000, v141
	global_load_lds_dwordx4 v[8:9], off
	v_lshl_add_u64 v[8:9], v[6:7], 0, s[4:5]
	s_mov_b32 m0, s52
	v_readfirstlane_b32 s52, v1
	v_add_u32_e32 v1, 0x4000, v142
	global_load_lds_dwordx4 v[8:9], off
	v_lshl_add_u64 v[8:9], v[4:5], 0, s[16:17]
	s_mov_b32 m0, s52
	v_readfirstlane_b32 s52, v1
	v_add_u32_e32 v1, 0x6000, v141
	global_load_lds_dwordx4 v[8:9], off
	v_lshl_add_u64 v[8:9], v[6:7], 0, s[16:17]
	s_mov_b32 m0, s52
	v_readfirstlane_b32 s52, v1
	v_add_u32_e32 v1, 0x6000, v142
	global_load_lds_dwordx4 v[8:9], off
	v_lshl_add_u64 v[4:5], v[4:5], 0, s[18:19]
	s_mov_b32 m0, s52
	v_readfirstlane_b32 s52, v1
	global_load_lds_dwordx4 v[4:5], off
	v_lshl_add_u64 v[4:5], v[6:7], 0, s[18:19]
	s_mov_b32 m0, s52
	v_ashrrev_i32_e32 v1, 1, v10
	global_load_lds_dwordx4 v[4:5], off
	v_and_b32_e32 v136, 15, v10
	v_and_b32_e32 v137, 0xffffffc0, v1
	v_lshrrev_b32_e32 v11, 4, v10
	v_or_b32_e32 v1, v137, v136
	v_and_b32_e32 v6, 7, v10
	v_bfe_u32 v135, v10, 6, 1
	v_bfe_u32 v128, v10, 4, 2
	v_lshl_add_u32 v138, v1, 7, 0
	v_bitop3_b32 v1, v11, v6, 3 bitop3:0x6c
	v_lshlrev_b32_e32 v4, 13, v135
	v_lshlrev_b32_e32 v5, 7, v136
	v_lshlrev_b32_e32 v143, 4, v1
	v_bitop3_b32 v1, v128, v6, 4 bitop3:0x36
	v_bitop3_b32 v0, v0, 7, v10 bitop3:0x48
	s_waitcnt vmcnt(0)
	v_add3_u32 v140, s8, v4, v5
	v_lshlrev_b32_e32 v139, 4, v1
	v_lshl_add_u64 v[4:5], s[2:3], 0, v[2:3]
	v_lshlrev_b32_e32 v6, 4, v0
	v_lshl_add_u64 v[0:1], v[2:3], 0, s[58:59]
	v_or_b32_e32 v4, v4, v6
	v_or_b32_e32 v0, v0, v6
	v_lshl_add_u64 v[130:131], s[72:73], 0, v[4:5]
	v_lshl_add_u64 v[132:133], s[72:73], 0, v[0:1]
	s_mov_b64 s[52:53], 0
	s_mov_b32 s2, 0
	v_mov_b32_e32 v40, 0
	v_mov_b32_e32 v41, v129
	v_mov_b32_e32 v42, v129
	v_mov_b32_e32 v43, v129
	v_mov_b32_e32 v44, 0
	v_mov_b32_e32 v45, v129
	v_mov_b32_e32 v46, v129
	v_mov_b32_e32 v47, v129
	v_mov_b32_e32 v0, 0
	v_mov_b32_e32 v1, v129
	v_mov_b32_e32 v2, v129
	v_mov_b32_e32 v3, v129
	v_mov_b32_e32 v4, 0
	v_mov_b32_e32 v5, v129
	v_mov_b32_e32 v6, v129
	v_mov_b32_e32 v7, v129
	v_mov_b32_e32 v64, 0
	v_mov_b32_e32 v65, v129
	v_mov_b32_e32 v66, v129
	v_mov_b32_e32 v67, v129
	v_mov_b32_e32 v68, 0
	v_mov_b32_e32 v69, v129
	v_mov_b32_e32 v70, v129
	v_mov_b32_e32 v71, v129
	v_mov_b32_e32 v72, 0
	v_mov_b32_e32 v73, v129
	v_mov_b32_e32 v74, v129
	v_mov_b32_e32 v75, v129
	v_mov_b32_e32 v76, 0
	v_mov_b32_e32 v77, v129
	v_mov_b32_e32 v78, v129
	v_mov_b32_e32 v79, v129
	v_mov_b32_e32 v8, 0
	v_mov_b32_e32 v9, v129
	v_mov_b32_e32 v10, v129
	v_mov_b32_e32 v11, v129
	v_mov_b32_e32 v12, 0
	v_mov_b32_e32 v13, v129
	v_mov_b32_e32 v14, v129
	v_mov_b32_e32 v15, v129
	v_mov_b32_e32 v16, 0
	v_mov_b32_e32 v17, v129
	v_mov_b32_e32 v18, v129
	v_mov_b32_e32 v19, v129
	v_mov_b32_e32 v20, 0
	v_mov_b32_e32 v21, v129
	v_mov_b32_e32 v22, v129
	v_mov_b32_e32 v23, v129
	v_mov_b32_e32 v80, 0
	v_mov_b32_e32 v81, v129
	v_mov_b32_e32 v82, v129
	v_mov_b32_e32 v83, v129
	v_mov_b32_e32 v84, 0
	v_mov_b32_e32 v85, v129
	v_mov_b32_e32 v86, v129
	v_mov_b32_e32 v87, v129
	v_mov_b32_e32 v88, 0
	v_mov_b32_e32 v89, v129
	v_mov_b32_e32 v90, v129
	v_mov_b32_e32 v91, v129
	v_mov_b32_e32 v92, 0
	v_mov_b32_e32 v93, v129
	v_mov_b32_e32 v94, v129
	v_mov_b32_e32 v95, v129
	v_mov_b32_e32 v24, 0
	v_mov_b32_e32 v25, v129
	v_mov_b32_e32 v26, v129
	v_mov_b32_e32 v27, v129
	v_mov_b32_e32 v28, 0
	v_mov_b32_e32 v29, v129
	v_mov_b32_e32 v30, v129
	v_mov_b32_e32 v31, v129
	v_mov_b32_e32 v32, 0
	v_mov_b32_e32 v33, v129
	v_mov_b32_e32 v34, v129
	v_mov_b32_e32 v35, v129
	v_mov_b32_e32 v36, 0
	v_mov_b32_e32 v37, v129
	v_mov_b32_e32 v38, v129
	v_mov_b32_e32 v39, v129
	v_mov_b32_e32 v96, 0
	v_mov_b32_e32 v97, v129
	v_mov_b32_e32 v98, v129
	v_mov_b32_e32 v99, v129
	v_mov_b32_e32 v100, 0
	v_mov_b32_e32 v101, v129
	v_mov_b32_e32 v102, v129
	v_mov_b32_e32 v103, v129
	v_mov_b32_e32 v104, 0
	v_mov_b32_e32 v105, v129
	v_mov_b32_e32 v106, v129
	v_mov_b32_e32 v107, v129
	v_mov_b32_e32 v108, 0
	v_mov_b32_e32 v109, v129
	v_mov_b32_e32 v110, v129
	v_mov_b32_e32 v111, v129
	v_mov_b32_e32 v48, 0
	v_mov_b32_e32 v49, v129
	v_mov_b32_e32 v50, v129
	v_mov_b32_e32 v51, v129
	v_mov_b32_e32 v52, 0
	v_mov_b32_e32 v53, v129
	v_mov_b32_e32 v54, v129
	v_mov_b32_e32 v55, v129
	v_mov_b32_e32 v56, 0
	v_mov_b32_e32 v57, v129
	v_mov_b32_e32 v58, v129
	v_mov_b32_e32 v59, v129
	v_mov_b32_e32 v60, 0
	v_mov_b32_e32 v61, v129
	v_mov_b32_e32 v62, v129
	v_mov_b32_e32 v63, v129
	v_mov_b32_e32 v112, 0
	v_mov_b32_e32 v113, v129
	v_mov_b32_e32 v114, v129
	v_mov_b32_e32 v115, v129
	v_mov_b32_e32 v116, 0
	v_mov_b32_e32 v117, v129
	v_mov_b32_e32 v118, v129
	v_mov_b32_e32 v119, v129
	v_mov_b32_e32 v120, 0
	v_mov_b32_e32 v121, v129
	v_mov_b32_e32 v122, v129
	v_mov_b32_e32 v123, v129
	v_mov_b32_e32 v124, 0
	v_mov_b32_e32 v125, v129
	v_mov_b32_e32 v126, v129
	v_mov_b32_e32 v127, v129
	s_waitcnt vmcnt(0) lgkmcnt(0)
	s_barrier
	v_readfirstlane_b32 s57, v141
	v_readfirstlane_b32 s58, v142
	s_and_b32 s59, s2, 0x8000
	s_xor_b32 s62, s59, 0x8000
	v_add3_u32 v157, v138, v143, s59
	v_add3_u32 v186, v140, v143, s59
	ds_read_b128 v[174:177], v157
	ds_read_b128 v[178:181], v157 offset:2048
	ds_read_b128 v[182:185], v157 offset:4096
	ds_read_b128 v[144:147], v157 offset:6144
	ds_read_b128 v[158:161], v186
	ds_read_b128 v[162:165], v186 offset:2048
	ds_read_b128 v[166:169], v186 offset:4096
	ds_read_b128 v[170:173], v186 offset:6144
	s_add_i32 s63, s57, s62
	s_add_i32 s64, s58, s62
	s_lshr_b32 s62, s23, 3
	s_and_b32 s62, s62, 7
	s_lshl_b32 s62, s62, 9
	s_add_i32 vcc_lo, s52, s62
	s_cmp_ge_u32 vcc_lo, 0xf80
	s_cselect_b32 vcc_hi, 0xf80, 0
	s_sub_i32 vcc_lo, vcc_lo, vcc_hi
	s_add_u32 s60, vcc_lo, s24
	s_addc_u32 s61, 0, s25
	s_add_i32 m0, s63, 0x0
	v_lshl_add_u64 v[242:243], v[130:131], 0, s[60:61]
	global_load_lds_dwordx4 v[242:243], off
	s_add_u32 s60, vcc_lo, s26
	s_addc_u32 s61, 0, s27
	s_add_i32 m0, s64, 0x0
	v_lshl_add_u64 v[242:243], v[132:133], 0, s[60:61]
	global_load_lds_dwordx4 v[242:243], off
	s_add_u32 s60, vcc_lo, s36
	s_addc_u32 s61, 0, s37
	s_add_i32 m0, s63, 0x2000
	v_lshl_add_u64 v[242:243], v[130:131], 0, s[60:61]
	global_load_lds_dwordx4 v[242:243], off
	s_add_u32 s60, vcc_lo, s38
	s_addc_u32 s61, 0, s39
	s_add_i32 m0, s64, 0x2000
	v_lshl_add_u64 v[242:243], v[132:133], 0, s[60:61]
	global_load_lds_dwordx4 v[242:243], off
	s_add_u32 s60, vcc_lo, s40
	s_addc_u32 s61, 0, s41
	s_add_i32 m0, s63, 0x4000
	v_lshl_add_u64 v[242:243], v[130:131], 0, s[60:61]
	global_load_lds_dwordx4 v[242:243], off
	s_add_u32 s60, vcc_lo, s42
	s_addc_u32 s61, 0, s43
	s_add_i32 m0, s64, 0x4000
	v_lshl_add_u64 v[242:243], v[132:133], 0, s[60:61]
	global_load_lds_dwordx4 v[242:243], off
	s_add_u32 s60, vcc_lo, s44
	s_addc_u32 s61, 0, s45
	s_add_i32 m0, s63, 0x6000
	v_lshl_add_u64 v[242:243], v[130:131], 0, s[60:61]
	global_load_lds_dwordx4 v[242:243], off
	s_add_u32 s60, vcc_lo, s48
	s_addc_u32 s61, 0, s49
	s_add_i32 m0, s64, 0x6000
	v_lshl_add_u64 v[242:243], v[132:133], 0, s[60:61]
	global_load_lds_dwordx4 v[242:243], off
.LBB0_698:
	s_and_b32 s59, s2, 0x8000
	s_add_i32 s2, s2, 0x8000
	v_add3_u32 v157, v138, v139, s59
	v_add3_u32 v186, v140, v143, s59
	v_add3_u32 v187, v140, v139, s59
	s_waitcnt lgkmcnt(3)
	v_mfma_f32_16x16x32_bf16 v[124:127], v[174:177], v[158:161], v[124:127]
	v_mfma_f32_16x16x32_bf16 v[108:111], v[178:181], v[158:161], v[108:111]
	v_mfma_f32_16x16x32_bf16 v[92:95], v[182:185], v[158:161], v[92:95]
	v_mfma_f32_16x16x32_bf16 v[76:79], v[144:147], v[158:161], v[76:79]
	ds_read_b128 v[158:161], v186 offset:16384
	ds_read_b128 v[148:151], v157
	s_waitcnt lgkmcnt(4)
	v_mfma_f32_16x16x32_bf16 v[120:123], v[174:177], v[162:165], v[120:123]
	v_mfma_f32_16x16x32_bf16 v[104:107], v[178:181], v[162:165], v[104:107]
	v_mfma_f32_16x16x32_bf16 v[88:91], v[182:185], v[162:165], v[88:91]
	v_mfma_f32_16x16x32_bf16 v[72:75], v[144:147], v[162:165], v[72:75]
	ds_read_b128 v[162:165], v186 offset:18432
	ds_read_b128 v[152:155], v157 offset:2048
	s_waitcnt lgkmcnt(5)
	v_mfma_f32_16x16x32_bf16 v[116:119], v[174:177], v[166:169], v[116:119]
	v_mfma_f32_16x16x32_bf16 v[100:103], v[178:181], v[166:169], v[100:103]
	v_mfma_f32_16x16x32_bf16 v[84:87], v[182:185], v[166:169], v[84:87]
	v_mfma_f32_16x16x32_bf16 v[68:71], v[144:147], v[166:169], v[68:71]
	ds_read_b128 v[166:169], v186 offset:20480
	ds_read_b128 v[244:247], v157 offset:4096
	s_waitcnt lgkmcnt(6)
	v_mfma_f32_16x16x32_bf16 v[112:115], v[174:177], v[170:173], v[112:115]
	v_mfma_f32_16x16x32_bf16 v[96:99], v[178:181], v[170:173], v[96:99]
	v_mfma_f32_16x16x32_bf16 v[80:83], v[182:185], v[170:173], v[80:83]
	v_mfma_f32_16x16x32_bf16 v[64:67], v[144:147], v[170:173], v[64:67]
	ds_read_b128 v[170:173], v186 offset:22528
	ds_read_b128 v[248:251], v157 offset:6144
	s_waitcnt lgkmcnt(7)
	v_mfma_f32_16x16x32_bf16 v[60:63], v[174:177], v[158:161], v[60:63]
	v_mfma_f32_16x16x32_bf16 v[36:39], v[178:181], v[158:161], v[36:39]
	v_mfma_f32_16x16x32_bf16 v[20:23], v[182:185], v[158:161], v[20:23]
	v_mfma_f32_16x16x32_bf16 v[4:7], v[144:147], v[158:161], v[4:7]
	ds_read_b128 v[158:161], v187
	s_waitcnt lgkmcnt(6)
	v_mfma_f32_16x16x32_bf16 v[56:59], v[174:177], v[162:165], v[56:59]
	v_mfma_f32_16x16x32_bf16 v[32:35], v[178:181], v[162:165], v[32:35]
	v_mfma_f32_16x16x32_bf16 v[16:19], v[182:185], v[162:165], v[16:19]
	v_mfma_f32_16x16x32_bf16 v[0:3], v[144:147], v[162:165], v[0:3]
	ds_read_b128 v[162:165], v187 offset:2048
	s_waitcnt lgkmcnt(5)
	v_mfma_f32_16x16x32_bf16 v[52:55], v[174:177], v[166:169], v[52:55]
	v_mfma_f32_16x16x32_bf16 v[28:31], v[178:181], v[166:169], v[28:31]
	v_mfma_f32_16x16x32_bf16 v[12:15], v[182:185], v[166:169], v[12:15]
	v_mfma_f32_16x16x32_bf16 v[44:47], v[144:147], v[166:169], v[44:47]
	ds_read_b128 v[166:169], v187 offset:4096
	s_waitcnt lgkmcnt(4)
	v_mfma_f32_16x16x32_bf16 v[48:51], v[174:177], v[170:173], v[48:51]
	v_mfma_f32_16x16x32_bf16 v[24:27], v[178:181], v[170:173], v[24:27]
	v_mfma_f32_16x16x32_bf16 v[8:11], v[182:185], v[170:173], v[8:11]
	v_mfma_f32_16x16x32_bf16 v[40:43], v[144:147], v[170:173], v[40:43]
	ds_read_b128 v[170:173], v187 offset:6144
	s_waitcnt lgkmcnt(3)
	v_mfma_f32_16x16x32_bf16 v[124:127], v[148:151], v[158:161], v[124:127]
	v_mfma_f32_16x16x32_bf16 v[108:111], v[152:155], v[158:161], v[108:111]
	v_mfma_f32_16x16x32_bf16 v[92:95], v[244:247], v[158:161], v[92:95]
	v_mfma_f32_16x16x32_bf16 v[76:79], v[248:251], v[158:161], v[76:79]
	ds_read_b128 v[158:161], v187 offset:16384
	s_waitcnt lgkmcnt(3)
	v_mfma_f32_16x16x32_bf16 v[120:123], v[148:151], v[162:165], v[120:123]
	v_mfma_f32_16x16x32_bf16 v[104:107], v[152:155], v[162:165], v[104:107]
	v_mfma_f32_16x16x32_bf16 v[88:91], v[244:247], v[162:165], v[88:91]
	v_mfma_f32_16x16x32_bf16 v[72:75], v[248:251], v[162:165], v[72:75]
	ds_read_b128 v[162:165], v187 offset:18432
	s_waitcnt lgkmcnt(3)
	v_mfma_f32_16x16x32_bf16 v[116:119], v[148:151], v[166:169], v[116:119]
	v_mfma_f32_16x16x32_bf16 v[100:103], v[152:155], v[166:169], v[100:103]
	v_mfma_f32_16x16x32_bf16 v[84:87], v[244:247], v[166:169], v[84:87]
	v_mfma_f32_16x16x32_bf16 v[68:71], v[248:251], v[166:169], v[68:71]
	ds_read_b128 v[166:169], v187 offset:20480
	s_waitcnt lgkmcnt(3)
	v_mfma_f32_16x16x32_bf16 v[112:115], v[148:151], v[170:173], v[112:115]
	v_mfma_f32_16x16x32_bf16 v[96:99], v[152:155], v[170:173], v[96:99]
	v_mfma_f32_16x16x32_bf16 v[80:83], v[244:247], v[170:173], v[80:83]
	v_mfma_f32_16x16x32_bf16 v[64:67], v[248:251], v[170:173], v[64:67]
	ds_read_b128 v[170:173], v187 offset:22528
	s_waitcnt lgkmcnt(3)
	v_mfma_f32_16x16x32_bf16 v[60:63], v[148:151], v[158:161], v[60:63]
	v_mfma_f32_16x16x32_bf16 v[36:39], v[152:155], v[158:161], v[36:39]
	v_mfma_f32_16x16x32_bf16 v[20:23], v[244:247], v[158:161], v[20:23]
	v_mfma_f32_16x16x32_bf16 v[4:7], v[248:251], v[158:161], v[4:7]
	s_add_u32 s52, s52, 0x80
	s_addc_u32 s53, s53, 0
	s_cmpk_eq_i32 s52, 0xf80
	s_waitcnt vmcnt(0) lgkmcnt(0)
	s_barrier
	s_cbranch_scc1 .Lgemm_698_exit
	s_xor_b32 s62, s59, 0x8000
	v_add3_u32 v157, v138, v143, s62
	v_add3_u32 v186, v140, v143, s62
	ds_read_b128 v[174:177], v157
	ds_read_b128 v[178:181], v157 offset:2048
	ds_read_b128 v[182:185], v157 offset:4096
	ds_read_b128 v[144:147], v157 offset:6144
	ds_read_b128 v[158:161], v186
	s_add_i32 s63, s57, s59
	s_add_i32 s64, s58, s59
	s_lshr_b32 s62, s23, 3
	s_and_b32 s62, s62, 7
	s_lshl_b32 s62, s62, 9
	s_add_i32 vcc_lo, s52, s62
	s_cmp_ge_u32 vcc_lo, 0xf80
	s_cselect_b32 vcc_hi, 0xf80, 0
	s_sub_i32 vcc_lo, vcc_lo, vcc_hi
	s_add_u32 s60, vcc_lo, s24
	s_addc_u32 s61, 0, s25
	s_add_i32 m0, s63, 0x0
	v_lshl_add_u64 v[242:243], v[130:131], 0, s[60:61]
	global_load_lds_dwordx4 v[242:243], off
	s_add_u32 s60, vcc_lo, s26
	s_addc_u32 s61, 0, s27
	s_add_i32 m0, s64, 0x0
	v_lshl_add_u64 v[242:243], v[132:133], 0, s[60:61]
	global_load_lds_dwordx4 v[242:243], off
	v_mfma_f32_16x16x32_bf16 v[56:59], v[148:151], v[162:165], v[56:59]
	v_mfma_f32_16x16x32_bf16 v[32:35], v[152:155], v[162:165], v[32:35]
	v_mfma_f32_16x16x32_bf16 v[16:19], v[244:247], v[162:165], v[16:19]
	v_mfma_f32_16x16x32_bf16 v[0:3], v[248:251], v[162:165], v[0:3]
	ds_read_b128 v[162:165], v186 offset:2048
	s_add_u32 s60, vcc_lo, s36
	s_addc_u32 s61, 0, s37
	s_add_i32 m0, s63, 0x2000
	v_lshl_add_u64 v[242:243], v[130:131], 0, s[60:61]
	global_load_lds_dwordx4 v[242:243], off
	s_add_u32 s60, vcc_lo, s38
	s_addc_u32 s61, 0, s39
	s_add_i32 m0, s64, 0x2000
	v_lshl_add_u64 v[242:243], v[132:133], 0, s[60:61]
	global_load_lds_dwordx4 v[242:243], off
	v_mfma_f32_16x16x32_bf16 v[52:55], v[148:151], v[166:169], v[52:55]
	v_mfma_f32_16x16x32_bf16 v[28:31], v[152:155], v[166:169], v[28:31]
	v_mfma_f32_16x16x32_bf16 v[12:15], v[244:247], v[166:169], v[12:15]
	v_mfma_f32_16x16x32_bf16 v[44:47], v[248:251], v[166:169], v[44:47]
	ds_read_b128 v[166:169], v186 offset:4096
	s_add_u32 s60, vcc_lo, s40
	s_addc_u32 s61, 0, s41
	s_add_i32 m0, s63, 0x4000
	v_lshl_add_u64 v[242:243], v[130:131], 0, s[60:61]
	global_load_lds_dwordx4 v[242:243], off
	s_add_u32 s60, vcc_lo, s42
	s_addc_u32 s61, 0, s43
	s_add_i32 m0, s64, 0x4000
	v_lshl_add_u64 v[242:243], v[132:133], 0, s[60:61]
	global_load_lds_dwordx4 v[242:243], off
	v_mfma_f32_16x16x32_bf16 v[48:51], v[148:151], v[170:173], v[48:51]
	v_mfma_f32_16x16x32_bf16 v[24:27], v[152:155], v[170:173], v[24:27]
	v_mfma_f32_16x16x32_bf16 v[8:11], v[244:247], v[170:173], v[8:11]
	v_mfma_f32_16x16x32_bf16 v[40:43], v[248:251], v[170:173], v[40:43]
	ds_read_b128 v[170:173], v186 offset:6144
	s_add_u32 s60, vcc_lo, s44
	s_addc_u32 s61, 0, s45
	s_add_i32 m0, s63, 0x6000
	v_lshl_add_u64 v[242:243], v[130:131], 0, s[60:61]
	global_load_lds_dwordx4 v[242:243], off
	s_add_u32 s60, vcc_lo, s48
	s_addc_u32 s61, 0, s49
	s_add_i32 m0, s64, 0x6000
	v_lshl_add_u64 v[242:243], v[132:133], 0, s[60:61]
	global_load_lds_dwordx4 v[242:243], off
	s_branch .LBB0_698
